# P1a small projection: 16 serialized load->MFMA round trips become 11-deep in flight; P2a loop-top counted wait; barrier + epilogue changes as before
# baseline (speedup 1.0000x reference)
; #define LAS __attribute__((address_space(3)))
; #define MFMA32(a, b, c) __builtin_amdgcn_mfma_f32_32x32x16_bf16((a), (b), (c), 0, 0, 0)
; __device__ __forceinline__ void small_unit(LAS unsigned char* lds, const bf16* h, const bf16* wsm, float* out, int unit) {
;     int tid_l = threadIdx.x; asm volatile("" : "+v"(tid_l));
;     const int tid = tid_l, lane = tid & 63, w = __builtin_amdgcn_readfirstlane(tid >> 6), r = lane & 31, hh = lane >> 5;
;     const int ct = w & 1, kq = w >> 1;
;     const bf16* ap = h + (size_t)(unit * 32 + r) * D + kq * 256 + 8 * hh;
;     const bf16* bp = wsm + (size_t)(32 * ct + r) * D + kq * 256 + 8 * hh;
;     f32x16 acc = zero16();
; #pragma unroll 8
;     for (int ks = 0; ks < 16; ++ks) acc = MFMA32(*(const bf16x8*)(ap + 16 * ks), *(const bf16x8*)(bp + 16 * ks), acc);
;     LAS float* red = (LAS float*)lds + (size_t)w * 1024 + lane;
;     if (kq != 0) {
; #pragma unroll
;         for (int i = 0; i < 16; ++i) red[i * 64] = acc[i]; }
.LBB0_107:
	global_load_dwordx4 v[36:39], v[20:21], off offset:-128
	global_load_dwordx4 v[40:43], v[18:19], off offset:-128
	global_load_dwordx4 v[44:47], v[20:21], off offset:-96
	global_load_dwordx4 v[48:51], v[18:19], off offset:-96
	global_load_dwordx4 v[52:55], v[20:21], off offset:-64
	global_load_dwordx4 v[56:59], v[18:19], off offset:-64
	global_load_dwordx4 v[60:63], v[20:21], off offset:-32
	global_load_dwordx4 v[64:67], v[18:19], off offset:-32
	global_load_dwordx4 v[68:71], v[20:21], off offset:0
	global_load_dwordx4 v[72:75], v[18:19], off offset:0
	global_load_dwordx4 v[76:79], v[20:21], off offset:32
	global_load_dwordx4 v[80:83], v[18:19], off offset:32
	global_load_dwordx4 v[84:87], v[20:21], off offset:64
	global_load_dwordx4 v[88:91], v[18:19], off offset:64
	global_load_dwordx4 v[92:95], v[20:21], off offset:96
	global_load_dwordx4 v[96:99], v[18:19], off offset:96
	global_load_dwordx4 v[100:103], v[20:21], off offset:128
	global_load_dwordx4 v[104:107], v[18:19], off offset:128
	global_load_dwordx4 v[108:111], v[20:21], off offset:160
	global_load_dwordx4 v[112:115], v[18:19], off offset:160
	global_load_dwordx4 v[116:119], v[20:21], off offset:192
	global_load_dwordx4 v[120:123], v[18:19], off offset:192
	s_waitcnt vmcnt(20)
	v_mfma_f32_32x32x16_bf16 v[2:17], v[36:39], v[40:43], v[2:17]
	global_load_dwordx4 v[36:39], v[20:21], off offset:224
	global_load_dwordx4 v[40:43], v[18:19], off offset:224
	s_waitcnt vmcnt(20)
	v_mfma_f32_32x32x16_bf16 v[2:17], v[44:47], v[48:51], v[2:17]
	global_load_dwordx4 v[44:47], v[20:21], off offset:256
	global_load_dwordx4 v[48:51], v[18:19], off offset:256
	s_waitcnt vmcnt(20)
	v_mfma_f32_32x32x16_bf16 v[2:17], v[52:55], v[56:59], v[2:17]
	global_load_dwordx4 v[52:55], v[20:21], off offset:288
	global_load_dwordx4 v[56:59], v[18:19], off offset:288
	s_waitcnt vmcnt(20)
	v_mfma_f32_32x32x16_bf16 v[2:17], v[60:63], v[64:67], v[2:17]
	global_load_dwordx4 v[60:63], v[20:21], off offset:320
	global_load_dwordx4 v[64:67], v[18:19], off offset:320
	s_waitcnt vmcnt(20)
	v_mfma_f32_32x32x16_bf16 v[2:17], v[68:71], v[72:75], v[2:17]
	global_load_dwordx4 v[68:71], v[20:21], off offset:352
	global_load_dwordx4 v[72:75], v[18:19], off offset:352
	s_waitcnt vmcnt(20)
	v_mfma_f32_32x32x16_bf16 v[2:17], v[76:79], v[80:83], v[2:17]
	s_waitcnt vmcnt(18)
	v_mfma_f32_32x32x16_bf16 v[2:17], v[84:87], v[88:91], v[2:17]
	s_waitcnt vmcnt(16)
	v_mfma_f32_32x32x16_bf16 v[2:17], v[92:95], v[96:99], v[2:17]
	s_waitcnt vmcnt(14)
	v_mfma_f32_32x32x16_bf16 v[2:17], v[100:103], v[104:107], v[2:17]
	s_waitcnt vmcnt(12)
	v_mfma_f32_32x32x16_bf16 v[2:17], v[108:111], v[112:115], v[2:17]
	s_waitcnt vmcnt(10)
	v_mfma_f32_32x32x16_bf16 v[2:17], v[116:119], v[120:123], v[2:17]
	s_waitcnt vmcnt(8)
	v_mfma_f32_32x32x16_bf16 v[2:17], v[36:39], v[40:43], v[2:17]
	s_waitcnt vmcnt(6)
	v_mfma_f32_32x32x16_bf16 v[2:17], v[44:47], v[48:51], v[2:17]
	s_waitcnt vmcnt(4)
	v_mfma_f32_32x32x16_bf16 v[2:17], v[52:55], v[56:59], v[2:17]
	s_waitcnt vmcnt(2)
	v_mfma_f32_32x32x16_bf16 v[2:17], v[60:63], v[64:67], v[2:17]
	s_waitcnt vmcnt(0)
	v_mfma_f32_32x32x16_bf16 v[2:17], v[68:71], v[72:75], v[2:17]
	s_lshl_b32 s2, s34, 12
	s_add_i32 s2, s2, 0
	v_and_b32_e32 v18, 63, v23
	s_cmpk_lt_u32 s38, 0x80
	v_lshl_add_u32 v20, v18, 2, s2
	s_cselect_b64 s[2:3], -1, 0
	s_and_b64 vcc, exec, s[2:3]
	s_cbranch_vccnz .LBB0_110
	s_nop 2
	ds_write2st64_b32 v20, v2, v3 offset1:1
	ds_write2st64_b32 v20, v4, v5 offset0:2 offset1:3
	ds_write2st64_b32 v20, v6, v7 offset0:4 offset1:5
	ds_write2st64_b32 v20, v8, v9 offset0:6 offset1:7
	ds_write2st64_b32 v20, v10, v11 offset0:8 offset1:9
	ds_write2st64_b32 v20, v12, v13 offset0:10 offset1:11
	ds_write2st64_b32 v20, v14, v15 offset0:12 offset1:13
	ds_write2st64_b32 v20, v16, v17 offset0:14 offset1:15

; #define LAS __attribute__((address_space(3)))
; __device__ __forceinline__ void gdn_prep_phase(LAS unsigned char* lds, const GdnPrepArgs& A, int bid, int G, const unsigned char* zero_page) {
;     ...
;         const LAS float* sc = (const LAS float*)(lds + L_SC);
;         const int j = 32 * ct + r; const float gfj = sc[j], gbj = sc[64 + j];
; #pragma unroll
;         for (int reg = 0; reg < 16; ++reg) {
;             const int i = 32 * rt + (reg & 3) + 8 * (reg >> 2) + 4 * hh; const float val = acc[reg];
;             const float ef = __expf(sc[i] - gfj), eb = __expf(sc[64 + i] - gbj);
;             if (which == 0) {
;                 const float lf = (i > j) ? sc[128 + i] * val * ef : 0.f, lb = (i < j) ? sc[192 + i] * val * eb : 0.f;
;                 ((LAS float*)(lds + L_LPF))[i * 64 + (j & 3) * 16 + (j >> 2)] = lf;
;                 const int i2 = 63 - i, j2 = 63 - j;
;                 ((LAS float*)(lds + L_LPB))[i2 * 64 + (j2 & 3) * 16 + (j2 >> 2)] = lb;
;             } else {
;                 const float af = (i >= j) ? QSCALE * val * ef : 0.f, ab = (i <= j) ? QSCALE * val * eb : 0.f;
;                 *(LAS unsigned short*)(lds + L_AF + i * AS_ + j * 2) = (unsigned short)(pkbf(af, 0.f) & 0xffffu);
;                 *(LAS unsigned short*)(lds + L_AB + i * AS_ + j * 2) = (unsigned short)(pkbf(ab, 0.f) & 0xffffu);
;             }
;         }
;     }
;     LBAR();
;     if (!(pflg & 16)) {
;         const int dir = w >> 2, li = (w & 3) * 64 + lane, j = li >> 2, q = li & 3;
;         const LAS float* LP = (const LAS float*)(lds + (dir ? L_LPB : L_LPF)) + q * 16;
;         float t[16];
; #pragma unroll
;         for (int a = 0; a < 16; ++a) t[a] = 0.f;
;         f32x4 lq[3][4];
;     ...
;         SOLVE_LD(0); SOLVE_LD(1);
; #pragma unroll
;         for (int i = 0; i < 64; ++i) {
;             if (i + 2 < 48) SOLVE_LD(i + 2);
;             else if (i + 1 >= 48 && i + 1 < 64) SOLVE_LD(i + 1);
;             float p0 = 0.f, p1 = 0.f;
; #pragma unroll
;             for (int a4 = 0; a4 < (i + 15) / 16; ++a4) { const f32x4 lv = lq[i % 3][a4];
;                 p0 = __builtin_fmaf(lv.x, t[4 * a4], p0); p1 = __builtin_fmaf(lv.y, t[4 * a4 + 1], p1); p0 = __builtin_fmaf(lv.z, t[4 * a4 + 2], p0); p1 = __builtin_fmaf(lv.w, t[4 * a4 + 3], p1); }
;             float p = quad_sum(p0 + p1);
;             const float ti = (i == j ? 1.f : 0.f) - p;
.LBB0_197:
	s_and_b64 vcc, exec, s[2:3]
	s_cbranch_vccnz .LBB0_362
	s_lshl_b32 s67, s34, 4
	v_writelane_b32 v254, s42, 55
	s_lshl_b32 s3, s34, 3
	s_ashr_i32 s2, s67, 31
	v_writelane_b32 v254, s43, 56
	s_cmp_lt_i32 s34, 51
	v_writelane_b32 v254, s2, 57
	s_cselect_b64 s[4:5], -1, 0
	s_ashr_i32 s2, s38, 7
	s_bfe_u32 s6, s38, 0x10006
	v_writelane_b32 v254, s4, 59
	s_cmpk_gt_u32 s38, 0xff
	s_mov_b32 s7, 0x11000
	v_writelane_b32 v254, s5, 60
	s_cselect_b64 s[4:5], -1, 0
	s_cmpk_lt_u32 s38, 0x100
	s_mov_b32 s39, 0x15800
	s_cselect_b32 s7, s7, 0xcc00
	s_cselect_b32 s39, s39, 0x19800
	s_lshl_b32 s40, s2, 5
	v_and_b32_e32 v4, 31, v7
	s_add_i32 s7, s7, 0
	s_and_b32 s40, s40, 32
	v_or_b32_e32 v3, s40, v4
	v_mov_b32_e32 v6, s7
	s_movk_i32 s42, 0x110
	s_lshl_b32 s7, s6, 5
	v_lshrrev_b32_e32 v5, 5, v18
	v_mad_u32_u24 v11, v3, s42, v6
	v_or_b32_e32 v3, s7, v4
	v_lshlrev_b32_e32 v12, 4, v5
	v_lshl_or_b32 v15, v5, 2, s40
	v_lshlrev_b32_e32 v5, 1, v3
	s_add_i32 s40, 0, 0x1d800
	s_add_i32 s41, 0, 0x11000
	v_add_u32_e32 v8, s40, v5
	s_add_i32 s40, 0, 0x1fc00
	v_mov_b32_e32 v6, s41
	v_add_u32_e32 v9, s40, v5
	v_lshlrev_b32_e32 v5, 6, v7
	v_mad_u32_u24 v14, v3, s42, v6
	v_and_b32_e32 v5, 0xc0, v5
	s_add_i32 s40, 0, 0x15800
	v_bitop3_b32 v6, s7, 60, v4 bitop3:0xc8
	v_bitop3_b32 v4, s7, 63, v4 bitop3:0x36
	v_add3_u32 v13, s40, v5, v6
	v_lshlrev_b32_e32 v5, 4, v4
	v_lshrrev_b32_e32 v4, 2, v4
	v_and_b32_e32 v57, 15, v7
	v_and_or_b32 v16, v5, 48, v4
	v_lshl_or_b32 v4, s2, 4, v57
	s_movk_i32 s2, 0x90
	v_mul_lo_u32 v4, v4, s2
	s_lshl_b32 s2, s6, 6
	v_lshrrev_b32_e32 v6, 1, v7
	s_and_b32 s38, s38, 0xc0
	v_and_b32_e32 v58, 24, v6
	s_add_i32 s2, s2, 0
	v_add3_u32 v33, s2, v4, v58
	v_lshrrev_b32_e32 v4, 2, v7
	s_add_i32 s6, s38, 0
	v_lshlrev_b32_e32 v2, 1, v18
	v_or_b32_e32 v17, s38, v18
	v_and_b32_e32 v59, 12, v4
	v_add_u32_e32 v62, s6, v58
	s_movk_i32 s6, 0x3fc
	v_readlane_b32 s42, v252, 62
	v_lshrrev_b32_e32 v32, 2, v17
	v_or_b32_e32 v4, s7, v59
	v_and_b32_e32 v60, 30, v2
	v_bitop3_b32 v2, v17, s6, v169 bitop3:0x6c
	v_mul_u32_u24_e32 v4, 0x110, v4
	v_add_u32_e32 v64, s42, v2
	v_lshlrev_b32_e32 v2, 1, v32
	v_add3_u32 v61, s41, v4, v60
	v_xor_b32_e32 v4, 0x7e, v2
	v_readlane_b32 s6, v252, 63
	s_or_b32 s52, s3, 7
	s_mulk_i32 s52, 0x300
	v_add_u32_e32 v34, s6, v4
	v_readlane_b32 s6, v254, 0
	s_or_b32 s53, s3, 1
	s_add_i32 s3, s52, 0xfffffd00
	v_add_u32_e32 v35, s6, v2
	v_cmp_gt_u32_e64 s[6:7], 2, v18
	v_and_b32_e32 v5, 3, v7
	s_add_i32 s39, s39, 0
	v_writelane_b32 v254, s6, 61
	v_and_b32_e32 v27, 64, v1
	v_lshl_add_u32 v56, v5, 6, s39
	v_writelane_b32 v254, s7, 62
	v_cmp_eq_u32_e64 s[6:7], 0, v18
	s_add_i32 s41, s41, s38
	v_bitop3_b32 v4, s38, v169, v18 bitop3:0xc8
	v_writelane_b32 v254, s6, 63
	v_xor_b32_e32 v21, 16, v1
	v_add_u32_e32 v27, 64, v27
	v_writelane_b32 v255, s7, 0
	v_writelane_b32 v255, s3, 1
	s_add_i32 s3, s52, 0xfffffa00
	v_writelane_b32 v255, s3, 3
	s_add_i32 s3, s52, 0xfffff700
	v_writelane_b32 v255, s3, 5
	s_add_i32 s3, s52, 0xfffff400
	v_writelane_b32 v255, s3, 7
	s_add_i32 s3, s52, 0xfffff100
	v_writelane_b32 v255, s3, 9
	s_add_i32 s3, s52, 0xffffee00
	v_writelane_b32 v255, s3, 11
	v_cmp_ge_u32_e64 s[38:39], v15, v3
	v_cmp_lt_i32_e32 vcc, v21, v27
	s_add_i32 s3, 0, 0x19800
	v_writelane_b32 v255, s38, 13
	v_cndmask_b32_e32 v21, v1, v21, vcc
	v_lshlrev_b32_e32 v69, 2, v21
	v_writelane_b32 v255, s39, 14
	v_cmp_gt_u32_e64 s[38:39], v15, v3
	v_xor_b32_e32 v21, 32, v1
	v_cmp_lt_i32_e32 vcc, v21, v27
	v_writelane_b32 v255, s38, 15
	v_lshlrev_b32_e32 v27, 6, v15
	v_add_u32_e32 v63, s41, v58
	v_writelane_b32 v255, s39, 16
	s_movk_i32 s38, 0xfc0
	v_bitop3_b32 v27, v16, s38, v27 bitop3:0x36
	v_lshl_add_u32 v73, v27, 2, s3
	v_or_b32_e32 v27, 1, v15
	v_lshl_add_u32 v74, v27, 2, s42
	v_cmp_lt_u32_e64 s[40:41], v27, v3
	v_lshlrev_b32_e32 v38, 8, v27
	v_lshlrev_b32_e32 v27, 6, v27
	v_cndmask_b32_e32 v21, v1, v21, vcc
	v_bitop3_b32 v27, v16, s38, v27 bitop3:0x36
	v_cmp_gt_u32_e32 vcc, 4, v17
	v_writelane_b32 v255, s40, 17
	v_lshl_add_u32 v75, v27, 2, s3
	v_or_b32_e32 v27, 2, v15
	v_cndmask_b32_e64 v104, 0, 1.0, vcc
	v_cmp_eq_u32_e32 vcc, 1, v32
	v_writelane_b32 v255, s41, 18
	v_cmp_lt_u32_e64 s[40:41], v27, v3
	v_cndmask_b32_e64 v105, 0, 1.0, vcc
	v_cmp_eq_u32_e32 vcc, 2, v32
	v_writelane_b32 v255, s40, 19
	v_lshl_add_u32 v76, v27, 2, s42
	v_cndmask_b32_e64 v106, 0, 1.0, vcc
	v_cmp_eq_u32_e32 vcc, 3, v32
	v_writelane_b32 v255, s41, 20
	v_cmp_gt_u32_e64 s[40:41], v27, v3
	v_lshlrev_b32_e32 v39, 8, v27
	v_lshlrev_b32_e32 v27, 6, v27
	v_cndmask_b32_e64 v107, 0, 1.0, vcc
	v_cmp_eq_u32_e32 vcc, 4, v32
	v_bitop3_b32 v27, v16, s38, v27 bitop3:0x36
	v_writelane_b32 v255, s40, 21
	v_cndmask_b32_e64 v109, 0, 1.0, vcc
	v_cmp_eq_u32_e32 vcc, 5, v32
	v_lshl_add_u32 v77, v27, 2, s3
	v_or_b32_e32 v27, 3, v15
	v_cndmask_b32_e64 v110, 0, 1.0, vcc
	v_cmp_eq_u32_e32 vcc, 6, v32
	v_writelane_b32 v255, s41, 22
	v_cmp_lt_u32_e64 s[40:41], v27, v3
	v_cndmask_b32_e64 v111, 0, 1.0, vcc
	v_cmp_eq_u32_e32 vcc, 7, v32
	v_writelane_b32 v255, s40, 23
	v_lshl_add_u32 v78, v27, 2, s42
	v_cndmask_b32_e64 v112, 0, 1.0, vcc
	v_cmp_eq_u32_e32 vcc, 8, v32
	v_writelane_b32 v255, s41, 24
	v_cmp_gt_u32_e64 s[40:41], v27, v3
	v_lshlrev_b32_e32 v40, 8, v27
	v_lshlrev_b32_e32 v27, 6, v27
	v_cndmask_b32_e64 v113, 0, 1.0, vcc
	v_cmp_eq_u32_e32 vcc, 9, v32
	v_bitop3_b32 v27, v16, s38, v27 bitop3:0x36
	v_writelane_b32 v255, s40, 25
	v_cndmask_b32_e64 v114, 0, 1.0, vcc
	v_cmp_eq_u32_e32 vcc, 10, v32
	v_lshl_add_u32 v79, v27, 2, s3
	v_or_b32_e32 v27, 8, v15
	v_cndmask_b32_e64 v115, 0, 1.0, vcc
	v_cmp_eq_u32_e32 vcc, 11, v32
	v_writelane_b32 v255, s41, 26
	v_cmp_lt_u32_e64 s[40:41], v27, v3
	v_cndmask_b32_e64 v116, 0, 1.0, vcc
; #define LAS __attribute__((address_space(3)))
; __device__ __forceinline__ void gdn_prep_phase(LAS unsigned char* lds, const GdnPrepArgs& A, int bid, int G, const unsigned char* zero_page) {
;     ...
;         const LAS float* sc = (const LAS float*)(lds + L_SC);
;         const int j = 32 * ct + r; const float gfj = sc[j], gbj = sc[64 + j];
; #pragma unroll
;         for (int reg = 0; reg < 16; ++reg) {
;             const int i = 32 * rt + (reg & 3) + 8 * (reg >> 2) + 4 * hh; const float val = acc[reg];
;             const float ef = __expf(sc[i] - gfj), eb = __expf(sc[64 + i] - gbj);
;             if (which == 0) {
;                 const float lf = (i > j) ? sc[128 + i] * val * ef : 0.f, lb = (i < j) ? sc[192 + i] * val * eb : 0.f;
;                 ((LAS float*)(lds + L_LPF))[i * 64 + (j & 3) * 16 + (j >> 2)] = lf;
;                 const int i2 = 63 - i, j2 = 63 - j;
;                 ((LAS float*)(lds + L_LPB))[i2 * 64 + (j2 & 3) * 16 + (j2 >> 2)] = lb;
;             } else {
;                 const float af = (i >= j) ? QSCALE * val * ef : 0.f, ab = (i <= j) ? QSCALE * val * eb : 0.f;
;                 *(LAS unsigned short*)(lds + L_AF + i * AS_ + j * 2) = (unsigned short)(pkbf(af, 0.f) & 0xffffu);
;                 *(LAS unsigned short*)(lds + L_AB + i * AS_ + j * 2) = (unsigned short)(pkbf(ab, 0.f) & 0xffffu);
;             }
;         }
;     }
;     LBAR();
;     if (!(pflg & 16)) {
;         const int dir = w >> 2, li = (w & 3) * 64 + lane, j = li >> 2, q = li & 3;
;         const LAS float* LP = (const LAS float*)(lds + (dir ? L_LPB : L_LPF)) + q * 16;
;         float t[16];
; #pragma unroll
;         for (int a = 0; a < 16; ++a) t[a] = 0.f;
;         f32x4 lq[3][4];
;     ...
;         SOLVE_LD(0); SOLVE_LD(1);
; #pragma unroll
;         for (int i = 0; i < 64; ++i) {
;             if (i + 2 < 48) SOLVE_LD(i + 2);
;             else if (i + 1 >= 48 && i + 1 < 64) SOLVE_LD(i + 1);
;             float p0 = 0.f, p1 = 0.f;
; #pragma unroll
;             for (int a4 = 0; a4 < (i + 15) / 16; ++a4) { const f32x4 lv = lq[i % 3][a4];
;                 p0 = __builtin_fmaf(lv.x, t[4 * a4], p0); p1 = __builtin_fmaf(lv.y, t[4 * a4 + 1], p1); p0 = __builtin_fmaf(lv.z, t[4 * a4 + 2], p0); p1 = __builtin_fmaf(lv.w, t[4 * a4 + 3], p1); }
;             float p = quad_sum(p0 + p1);
;             const float ti = (i == j ? 1.f : 0.f) - p;
	v_cmp_eq_u32_e32 vcc, 12, v32
	v_writelane_b32 v255, s40, 27
	v_lshl_add_u32 v80, v27, 2, s42
	v_cndmask_b32_e64 v118, 0, 1.0, vcc
	v_cmp_eq_u32_e32 vcc, 13, v32
	v_writelane_b32 v255, s41, 28
	v_cmp_gt_u32_e64 s[40:41], v27, v3
	v_lshlrev_b32_e32 v41, 8, v27
	v_lshlrev_b32_e32 v27, 6, v27
	v_cndmask_b32_e64 v119, 0, 1.0, vcc
	v_cmp_eq_u32_e32 vcc, 14, v32
	v_bitop3_b32 v27, v16, s38, v27 bitop3:0x36
	v_writelane_b32 v255, s40, 29
	v_cndmask_b32_e64 v120, 0, 1.0, vcc
	v_cmp_eq_u32_e32 vcc, 15, v32
	v_lshl_add_u32 v81, v27, 2, s3
	v_or_b32_e32 v27, 9, v15
	v_cndmask_b32_e64 v121, 0, 1.0, vcc
	v_cmp_eq_u32_e32 vcc, 16, v32
	v_writelane_b32 v255, s41, 30
	v_cmp_lt_u32_e64 s[40:41], v27, v3
	v_cndmask_b32_e64 v122, 0, 1.0, vcc
	v_cmp_eq_u32_e32 vcc, 17, v32
	v_writelane_b32 v255, s40, 31
	v_lshl_add_u32 v82, v27, 2, s42
	v_cndmask_b32_e64 v123, 0, 1.0, vcc
	v_cmp_eq_u32_e32 vcc, 18, v32
	v_writelane_b32 v255, s41, 32
	v_cmp_gt_u32_e64 s[40:41], v27, v3
	v_lshlrev_b32_e32 v42, 8, v27
	v_lshlrev_b32_e32 v27, 6, v27
	v_cndmask_b32_e64 v124, 0, 1.0, vcc
	v_cmp_eq_u32_e32 vcc, 19, v32
	v_bitop3_b32 v27, v16, s38, v27 bitop3:0x36
	v_writelane_b32 v255, s40, 33
	v_cndmask_b32_e64 v125, 0, 1.0, vcc
	v_cmp_eq_u32_e32 vcc, 20, v32
	v_lshl_add_u32 v83, v27, 2, s3
	v_or_b32_e32 v27, 10, v15
	v_cndmask_b32_e64 v126, 0, 1.0, vcc
	v_cmp_eq_u32_e32 vcc, 21, v32
	v_writelane_b32 v255, s41, 34
	v_cmp_lt_u32_e64 s[40:41], v27, v3
	v_cndmask_b32_e64 v127, 0, 1.0, vcc
	v_cmp_eq_u32_e32 vcc, 22, v32
	v_writelane_b32 v255, s40, 35
	v_lshl_add_u32 v84, v27, 2, s42
	v_cndmask_b32_e64 v128, 0, 1.0, vcc
	v_cmp_eq_u32_e32 vcc, 23, v32
	v_writelane_b32 v255, s41, 36
	v_cmp_gt_u32_e64 s[40:41], v27, v3
	v_lshlrev_b32_e32 v43, 8, v27
	v_lshlrev_b32_e32 v27, 6, v27
	v_cndmask_b32_e64 v129, 0, 1.0, vcc
	v_cmp_eq_u32_e32 vcc, 24, v32
	v_bitop3_b32 v27, v16, s38, v27 bitop3:0x36
	v_writelane_b32 v255, s40, 37
	v_cndmask_b32_e64 v136, 0, 1.0, vcc
	v_cmp_eq_u32_e32 vcc, 25, v32
	v_lshl_add_u32 v85, v27, 2, s3
	v_or_b32_e32 v27, 11, v15
	v_cndmask_b32_e64 v137, 0, 1.0, vcc
	v_cmp_eq_u32_e32 vcc, 26, v32
	v_writelane_b32 v255, s41, 38
	v_cmp_lt_u32_e64 s[40:41], v27, v3
	v_cndmask_b32_e64 v138, 0, 1.0, vcc
	v_cmp_eq_u32_e32 vcc, 27, v32
	v_writelane_b32 v255, s40, 39
	v_lshl_add_u32 v86, v27, 2, s42
	v_cndmask_b32_e64 v139, 0, 1.0, vcc
	v_cmp_eq_u32_e32 vcc, 28, v32
	v_writelane_b32 v255, s41, 40
	v_cmp_gt_u32_e64 s[40:41], v27, v3
	v_lshlrev_b32_e32 v44, 8, v27
	v_lshlrev_b32_e32 v27, 6, v27
	v_cndmask_b32_e64 v140, 0, 1.0, vcc
	v_cmp_eq_u32_e32 vcc, 29, v32
	v_bitop3_b32 v27, v16, s38, v27 bitop3:0x36
	v_writelane_b32 v255, s40, 41
	v_cndmask_b32_e64 v141, 0, 1.0, vcc
	v_cmp_eq_u32_e32 vcc, 30, v32
	v_lshl_add_u32 v87, v27, 2, s3
	v_or_b32_e32 v27, 16, v15
	v_cndmask_b32_e64 v142, 0, 1.0, vcc
	v_cmp_eq_u32_e32 vcc, 31, v32
	v_writelane_b32 v255, s41, 42
	v_cmp_lt_u32_e64 s[40:41], v27, v3
	v_cndmask_b32_e64 v143, 0, 1.0, vcc
	v_cmp_eq_u32_e32 vcc, 32, v32
	v_writelane_b32 v255, s40, 43
	v_lshl_add_u32 v88, v27, 2, s42
	v_cndmask_b32_e64 v144, 0, 1.0, vcc
	v_cmp_eq_u32_e32 vcc, 33, v32
	v_writelane_b32 v255, s41, 44
	v_cmp_gt_u32_e64 s[40:41], v27, v3
	v_lshlrev_b32_e32 v45, 8, v27
	v_lshlrev_b32_e32 v27, 6, v27
	v_cndmask_b32_e64 v145, 0, 1.0, vcc
	v_cmp_eq_u32_e32 vcc, 34, v32
	v_bitop3_b32 v27, v16, s38, v27 bitop3:0x36
	v_or_b32_e32 v46, 17, v15
	v_cndmask_b32_e64 v146, 0, 1.0, vcc
	v_cmp_eq_u32_e32 vcc, 35, v32
	v_lshl_add_u32 v89, v27, 2, s3
	v_lshlrev_b32_e32 v27, 6, v46
	v_cndmask_b32_e64 v147, 0, 1.0, vcc
	v_cmp_eq_u32_e32 vcc, 36, v32
	v_bitop3_b32 v27, v16, s38, v27 bitop3:0x36
	v_or_b32_e32 v48, 18, v15
	v_cndmask_b32_e64 v148, 0, 1.0, vcc
	v_cmp_eq_u32_e32 vcc, 37, v32
	v_lshl_add_u32 v91, v27, 2, s3
	v_lshlrev_b32_e32 v27, 6, v48
	v_cndmask_b32_e64 v149, 0, 1.0, vcc
	v_cmp_eq_u32_e32 vcc, 38, v32
	v_bitop3_b32 v27, v16, s38, v27 bitop3:0x36
	v_or_b32_e32 v230, 19, v15
	v_cndmask_b32_e64 v150, 0, 1.0, vcc
	v_cmp_eq_u32_e32 vcc, 39, v32
	v_lshl_add_u32 v93, v27, 2, s3
	v_lshlrev_b32_e32 v27, 6, v230
	v_cndmask_b32_e64 v151, 0, 1.0, vcc
	v_cmp_eq_u32_e32 vcc, 40, v32
	v_bitop3_b32 v27, v16, s38, v27 bitop3:0x36
	v_or_b32_e32 v231, 24, v15
	v_cndmask_b32_e64 v152, 0, 1.0, vcc
	v_cmp_eq_u32_e32 vcc, 41, v32
	v_lshl_add_u32 v95, v27, 2, s3
	v_lshlrev_b32_e32 v27, 6, v231
	v_cndmask_b32_e64 v153, 0, 1.0, vcc
	v_cmp_eq_u32_e32 vcc, 42, v32
	v_bitop3_b32 v27, v16, s38, v27 bitop3:0x36
	v_or_b32_e32 v232, 25, v15
	v_cndmask_b32_e64 v154, 0, 1.0, vcc
	v_cmp_eq_u32_e32 vcc, 43, v32
	v_lshl_add_u32 v97, v27, 2, s3
	v_lshlrev_b32_e32 v27, 6, v232
	v_cndmask_b32_e64 v155, 0, 1.0, vcc
	v_cmp_eq_u32_e32 vcc, 44, v32
	v_bitop3_b32 v27, v16, s38, v27 bitop3:0x36
	v_or_b32_e32 v233, 26, v15
	v_cndmask_b32_e64 v156, 0, 1.0, vcc
	v_cmp_eq_u32_e32 vcc, 45, v32
	v_lshl_add_u32 v99, v27, 2, s3
	v_lshlrev_b32_e32 v27, 6, v233
	v_cndmask_b32_e64 v157, 0, 1.0, vcc
	v_cmp_eq_u32_e32 vcc, 46, v32
	v_lshl_add_u32 v72, v15, 2, s42
	v_cmp_lt_u32_e64 s[6:7], v15, v3
	v_mul_u32_u24_e32 v36, 0x90, v15
	v_lshlrev_b32_e32 v37, 8, v15
	v_bitop3_b32 v27, v16, s38, v27 bitop3:0x36
	v_or_b32_e32 v15, 27, v15
	v_cndmask_b32_e64 v158, 0, 1.0, vcc
	v_cmp_eq_u32_e32 vcc, 47, v32
	v_lshl_add_u32 v101, v27, 2, s3
	v_lshlrev_b32_e32 v27, 6, v15
	v_cndmask_b32_e64 v159, 0, 1.0, vcc
	v_cmp_eq_u32_e32 vcc, 48, v32
	v_bitop3_b32 v26, v7, 63, 3 bitop3:0x6c
	v_bitop3_b32 v16, v16, s38, v27 bitop3:0x36
	v_cndmask_b32_e64 v160, 0, 1.0, vcc
	v_cmp_eq_u32_e32 vcc, 49, v32
	v_lshl_add_u32 v103, v16, 2, s3
	v_mul_u32_u24_e32 v16, 0x90, v26
	v_bitop3_b32 v26, v7, 55, 3 bitop3:0x6c
	v_cndmask_b32_e64 v161, 0, 1.0, vcc
; __device__ __forceinline__ void gdn_prep_phase(LAS unsigned char* lds, const GdnPrepArgs& A, int bid, int G, const unsigned char* zero_page) {
;     ...
;   for (; unit < nunits; unit += G) {
;     const int h = (unit / NCH) % 8;
;     unsigned char* blob = A.blob + (size_t)unit * BLOB;
;     __builtin_amdgcn_s_waitcnt(0x0F70);
;     __syncthreads();
	v_cmp_eq_u32_e32 vcc, 50, v32
	v_mul_u32_u24_e32 v210, 0x90, v26
	v_bitop3_b32 v26, v7, 51, 3 bitop3:0x6c
	v_cndmask_b32_e64 v162, 0, 1.0, vcc
	v_cmp_eq_u32_e32 vcc, 51, v32
	v_mul_u32_u24_e32 v211, 0x90, v26
	v_bitop3_b32 v26, v7, 47, 3 bitop3:0x6c
	v_cndmask_b32_e64 v163, 0, 1.0, vcc
	v_cmp_eq_u32_e32 vcc, 52, v32
	v_mul_u32_u24_e32 v212, 0x90, v26
	v_bitop3_b32 v26, v7, 43, 3 bitop3:0x6c
	v_readlane_b32 s38, v251, 39
	v_cndmask_b32_e64 v173, 0, 1.0, vcc
	v_cmp_eq_u32_e32 vcc, 53, v32
	v_add_u32_e32 v54, 0, v130
	v_mul_u32_u24_e32 v213, 0x90, v26
	v_bitop3_b32 v26, v7, 39, 3 bitop3:0x6c
	v_lshlrev_b32_e32 v130, 3, v18
	v_readlane_b32 s39, v251, 40
	v_cndmask_b32_e64 v174, 0, 1.0, vcc
	v_cmp_eq_u32_e32 vcc, 54, v32
	v_writelane_b32 v255, s40, 45
	v_mul_u32_u24_e32 v214, 0x90, v26
	v_bitop3_b32 v26, v7, 35, 3 bitop3:0x6c
	v_lshl_add_u64 v[28:29], s[38:39], 0, v[130:131]
	v_readlane_b32 s38, v251, 41
	v_cndmask_b32_e64 v175, 0, 1.0, vcc
	v_cmp_eq_u32_e32 vcc, 55, v32
	v_writelane_b32 v255, s41, 46
	v_mul_u32_u24_e32 v215, 0x90, v26
	v_bitop3_b32 v26, v7, 31, 3 bitop3:0x6c
	v_readlane_b32 s39, v251, 42
	s_add_i32 s41, s34, 8
	v_cndmask_b32_e64 v176, 0, 1.0, vcc
	v_cmp_eq_u32_e32 vcc, 56, v32
	v_mul_u32_u24_e32 v216, 0x90, v26
	v_bitop3_b32 v26, v7, 27, 3 bitop3:0x6c
	v_lshl_add_u64 v[30:31], s[38:39], 0, v[130:131]
	s_lshl_b32 s38, s41, 2
	v_cndmask_b32_e64 v177, 0, 1.0, vcc
	v_cmp_eq_u32_e32 vcc, 57, v32
	v_mul_u32_u24_e32 v217, 0x90, v26
	v_bitop3_b32 v26, v7, 23, 3 bitop3:0x6c
	v_readlane_b32 s68, v250, 10
	s_and_b32 s38, s38, 0xffffff0
	v_cndmask_b32_e64 v178, 0, 1.0, vcc
	v_cmp_eq_u32_e32 vcc, 58, v32
	v_mul_u32_u24_e32 v218, 0x90, v26
	v_bitop3_b32 v26, v7, 19, 3 bitop3:0x6c
	v_readlane_b32 s72, v250, 14
	s_lshl_b32 s40, s34, 2
	v_or_b32_e32 v117, s38, v57
	s_lshl_b32 s38, s41, 10
	v_cndmask_b32_e64 v179, 0, 1.0, vcc
	v_cmp_eq_u32_e32 vcc, 59, v32
	s_lshl_b32 s41, s41, 4
	s_lshl_b32 s2, s34, 10
	v_mul_u32_u24_e32 v219, 0x90, v26
	v_bitop3_b32 v26, v7, 15, 3 bitop3:0x6c
	s_and_b32 s3, s40, 0xffffff0
	v_cndmask_b32_e64 v180, 0, 1.0, vcc
	v_cmp_eq_u32_e32 vcc, 60, v32
	s_and_b32 s72, s41, 0xffffffe0
	s_add_i32 s41, s34, -8
	v_mul_u32_u24_e32 v220, 0x90, v26
	v_bitop3_b32 v26, v7, 11, 3 bitop3:0x6c
	v_or_b32_e32 v108, s3, v57
	s_ashr_i32 s3, s2, 31
	v_cndmask_b32_e64 v181, 0, 1.0, vcc
	v_cmp_eq_u32_e32 vcc, 61, v32
	v_writelane_b32 v255, s41, 47
	v_lshrrev_b32_e32 v10, 4, v18
	v_bitop3_b32 v17, v7, 59, 3 bitop3:0x6c
	v_mul_u32_u24_e32 v221, 0x90, v26
	v_bitop3_b32 v26, v7, 7, 3 bitop3:0x6c
	v_bitop3_b32 v7, v7, 3, v7 bitop3:0xc
	v_readlane_b32 s70, v250, 12
	v_cndmask_b32_e64 v182, 0, 1.0, vcc
	v_cmp_eq_u32_e32 vcc, 62, v32
	v_writelane_b32 v255, s2, 48
	v_lshlrev_b32_e32 v22, 4, v18
	v_add_u32_e32 v65, s42, v4
	v_or_b32_e32 v2, 64, v18
	v_or_b32_e32 v4, 0x80, v18
	v_or_b32_e32 v6, 0xc0, v18
	v_lshlrev_b32_e32 v47, 8, v46
	v_lshlrev_b32_e32 v49, 8, v48
	v_lshlrev_b32_e32 v203, 8, v230
	v_lshlrev_b32_e32 v204, 8, v231
	v_lshlrev_b32_e32 v205, 8, v232
	v_lshlrev_b32_e32 v206, 8, v233
	v_lshlrev_b32_e32 v207, 8, v15
	v_mul_u32_u24_e32 v17, 0x90, v17
	v_mul_u32_u24_e32 v222, 0x90, v26
	v_mul_u32_u24_e32 v7, 0x90, v7
	v_mul_u32_u24_e32 v224, 0x90, v5
	v_readlane_b32 s69, v250, 11
	v_readlane_b32 s71, v250, 13
	v_readlane_b32 s74, v250, 16
	v_readlane_b32 s75, v250, 17
	v_readlane_b32 s76, v250, 18
	v_readlane_b32 s77, v250, 19
	v_readlane_b32 s78, v250, 20
	v_readlane_b32 s79, v250, 21
	v_readlane_b32 s80, v250, 22
	v_readlane_b32 s81, v250, 23
	s_movk_i32 s70, 0x110
	v_cndmask_b32_e64 v183, 0, 1.0, vcc
	v_cmp_eq_u32_e32 vcc, 63, v32
	v_or_b32_e32 v189, s40, v10
	v_writelane_b32 v255, s3, 49
	s_add_i32 s40, s2, 0
	v_lshlrev_b32_e32 v20, 8, v18
	v_and_b32_e32 v24, 0xf0, v22
	v_mov_b32_e32 v25, v131
	v_lshl_add_u32 v55, v3, 2, s42
	v_mov_b32_e32 v23, v131
	v_lshl_add_u32 v66, v2, 2, s42
	v_lshl_add_u32 v67, v4, 2, s42
	v_lshl_add_u32 v68, v6, 2, s42
	v_lshlrev_b32_e32 v70, 2, v21
	s_mulk_i32 s53, 0x110
	v_add_u32_e32 v71, 0x11000, v54
	v_mov_b32_e32 v21, v131
	v_lshl_add_u32 v90, v46, 2, s42
	v_lshl_add_u32 v92, v48, 2, s42
	v_lshl_add_u32 v94, v230, 2, s42
	v_lshl_add_u32 v96, v231, 2, s42
	v_lshl_add_u32 v98, v232, 2, s42
	v_lshl_add_u32 v100, v233, 2, s42
	v_lshl_add_u32 v102, v15, 2, s42
	v_lshl_add_u64 v[26:27], s[74:75], 0, v[130:131]
	v_mul_lo_u32 v108, v108, s70
	v_mul_lo_u32 v117, v117, s70
	s_ashr_i32 s39, s38, 31
	v_cndmask_b32_e64 v184, 0, 1.0, vcc
	s_and_b32 s71, s67, 0xffffffe0
	v_add_u32_e32 v185, 0x1d800, v33
	v_add_u32_e32 v186, 0x1d820, v33
	v_add_u32_e32 v187, 0x1fc00, v33
	v_add_u32_e32 v188, 0x1fc20, v33
	v_writelane_b32 v255, s40, 50
	v_add_u32_e32 v190, v11, v12
	v_add_u32_e32 v191, v14, v12
	v_add_u32_e32 v192, v13, v37
	v_add_u32_e32 v193, v13, v38
	v_add_u32_e32 v194, v13, v39
	v_add_u32_e32 v195, v13, v40
	v_add_u32_e32 v196, v13, v41
	v_add_u32_e32 v197, v13, v42
	v_add_u32_e32 v198, v13, v43
	v_add_u32_e32 v199, v13, v44
	v_add_u32_e32 v200, v13, v45
	v_add_u32_e32 v201, v13, v47
	v_add_u32_e32 v202, v13, v49
	v_add_u32_e32 v203, v13, v203
	v_add_u32_e32 v204, v13, v204
	v_add_u32_e32 v205, v13, v205
	v_add_u32_e32 v206, v13, v206
	v_add_u32_e32 v207, v13, v207
	v_add_u32_e32 v208, v34, v16
	v_add_u32_e32 v209, v34, v17
	v_add_u32_e32 v210, v34, v210
	v_add_u32_e32 v211, v34, v211
	v_add_u32_e32 v212, v34, v212
	v_add_u32_e32 v213, v34, v213
	v_add_u32_e32 v214, v34, v214
	v_add_u32_e32 v215, v34, v215
	v_add_u32_e32 v216, v34, v216
	v_add_u32_e32 v217, v34, v217
	v_add_u32_e32 v218, v34, v218
	v_add_u32_e32 v219, v34, v219
	v_add_u32_e32 v220, v34, v220
	v_add_u32_e32 v221, v34, v221
	v_add_u32_e32 v222, v34, v222
	v_add_u32_e32 v223, v34, v7
	v_add_u32_e32 v224, v35, v224
	v_lshlrev_b32_e32 v225, 2, v2
	v_lshlrev_b32_e32 v226, 2, v4
	v_lshlrev_b32_e32 v227, 2, v6
	v_add_u32_e32 v228, v8, v36
	v_add_u32_e32 v229, v9, v36
	s_mov_b32 s56, s85
	v_cmp_lt_u32_e64 s[74:75], v46, v3
	v_cmp_gt_u32_e64 s[76:77], v46, v3
	v_cmp_lt_u32_e64 s[58:59], v48, v3
	v_cmp_gt_u32_e64 s[60:61], v48, v3
	v_cmp_lt_u32_e64 s[62:63], v230, v3
	v_cmp_gt_u32_e64 s[64:65], v230, v3
	v_cmp_lt_u32_e64 s[84:85], v231, v3
	v_cmp_gt_u32_e64 s[78:79], v231, v3
	v_cmp_lt_u32_e64 s[80:81], v232, v3
	v_cmp_gt_u32_e64 s[26:27], v232, v3
	v_cmp_lt_u32_e64 s[28:29], v233, v3
	v_cmp_gt_u32_e64 s[30:31], v233, v3
	v_cmp_lt_u32_e64 s[24:25], v15, v3
	v_cmp_gt_u32_e64 s[36:37], v15, v3
	v_cmp_eq_u32_e64 s[86:87], 0, v5
	v_cmp_eq_u32_e64 s[88:89], 1, v5
	v_cmp_eq_u32_e64 s[90:91], 2, v5
	v_cmp_eq_u32_e64 s[92:93], 3, v5
	s_mov_b32 s68, 0x55555556
	s_movk_i32 s69, 0x800
	v_readlane_b32 s73, v250, 15
	v_readlane_b32 s82, v250, 24
	v_readlane_b32 s83, v250, 25
	s_waitcnt vmcnt(0)
	s_nop 0
	s_branch .LBB0_201

; #define LAS __attribute__((address_space(3)))
; __device__ __forceinline__ unsigned pkbf(float a, float b) { bf16x2_t v = __builtin_convertvector((f32x2_t){a, b}, bf16x2_t); return __builtin_bit_cast(unsigned, v); }
; __device__ __forceinline__ void gdn_prep_phase(LAS unsigned char* lds, const GdnPrepArgs& A, int bid, int G, const unsigned char* zero_page) {
;     ...
;     __builtin_amdgcn_s_waitcnt(0x0F70);
;     __syncthreads();
;     if (!(pflg & 32)) {
;         const int p0 = 8 * w;
; #pragma unroll
;         for (int m = 0; m < 3; ++m) {
;             float wc[5][2];
; #pragma unroll
;             for (int tau = 0; tau < 5; ++tau) { const f32x2_t t2 = *(const f32x2_t*)(A.conv_w + tau * 3072 + m * 1024 + h * 128 + 2 * lane); wc[tau][0] = t2.x; wc[tau][1] = t2.y; }
;             float in[12][2];
; #pragma unroll
;             for (int i = 0; i < 12; ++i) { const unsigned u = *(const LAS unsigned*)(lds + L_PRE + ((p0 + i) * 3 + m) * 256 + lane * 4); in[i][0] = bflo(u); in[i][1] = bfhi(u); }
;             float y[8][2];
; #pragma unroll
;             for (int pp = 0; pp < 8; ++pp)
; #pragma unroll
;                 for (int c = 0; c < 2; ++c) { float s = 0.f;
; #pragma unroll
;                     for (int tau = 0; tau < 5; ++tau) s += wc[tau][c] * in[pp + tau][c];
;                     y[pp][c] = s * __builtin_amdgcn_rcpf(1.0f + __builtin_amdgcn_exp2f(-1.4426950408889634f * s)); }
;             if (m < 2) {
; #pragma unroll
;                 for (int pp = 0; pp < 8; ++pp) { float ss = row16_sum(y[pp][0] * y[pp][0] + y[pp][1] * y[pp][1]); ss += __shfl_xor(ss, 16); ss += __shfl_xor(ss, 32); const float rn = __builtin_amdgcn_rsqf(ss + EPS);
;                     *(LAS unsigned*)(lds + (m == 0 ? L_QN : L_KN) + (p0 + pp) * QS_ + lane * 4) = pkbf(y[pp][0] * rn, y[pp][1] * rn); }
.LBB0_201:
	s_ashr_i32 s40, s56, 31
	s_lshr_b32 s40, s40, 27
	s_add_i32 s40, s56, s40
	s_ashr_i32 s40, s40, 5
	s_lshr_b32 s41, s40, 29
	s_add_i32 s41, s40, s41
	s_and_b32 s41, s41, 0x1fffff8
	s_sub_i32 s42, s40, s41
	s_mul_i32 s40, s56, 0x18800
	v_readlane_b32 s44, v253, 63
	s_mul_hi_i32 s41, s56, 0x18800
	v_readlane_b32 s45, v252, 0
	s_add_u32 s40, s44, s40
	s_addc_u32 s41, s45, s41
	s_lshl_b32 s42, s42, 7
	s_ashr_i32 s43, s42, 31
	s_add_u32 s94, s40, s67
	v_readlane_b32 s44, v254, 57
	s_addc_u32 s95, s41, s44
	s_lshl_b64 s[42:43], s[42:43], 2
	v_lshl_add_u64 v[32:33], v[26:27], 0, s[42:43]
	s_movk_i32 s46, 0x3000
	v_add_co_u32_e32 v6, vcc, s46, v32
	s_movk_i32 s45, 0x6000
	s_nop 0
	v_addc_co_u32_e32 v7, vcc, 0, v33, vcc
	v_add_co_u32_e32 v10, vcc, s45, v32
	s_mov_b32 s47, 0x9000
	s_nop 0
	v_addc_co_u32_e32 v11, vcc, 0, v33, vcc
	s_waitcnt vmcnt(2) lgkmcnt(0)
	s_barrier
	global_load_dwordx2 v[2:3], v[32:33], off
	s_mul_i32 s44, s34, 0x1800
	v_add_co_u32_e32 v14, vcc, s47, v32
	global_load_dwordx2 v[6:7], v[6:7], off
	v_add_u32_e32 v130, s44, v54
	v_addc_co_u32_e32 v15, vcc, 0, v33, vcc
	s_mov_b32 s44, 0xc000
	global_load_dwordx2 v[10:11], v[10:11], off
	v_readlane_b32 s48, v255, 1
	global_load_dwordx2 v[14:15], v[14:15], off
	v_add_co_u32_e32 v32, vcc, s44, v32
	v_add_u32_e32 v233, s48, v54
	s_nop 0
	v_addc_co_u32_e32 v33, vcc, 0, v33, vcc
	global_load_dwordx2 v[32:33], v[32:33], off
	v_readlane_b32 s48, v255, 3
	ds_read_b32 v8, v130 offset:6144
	ds_read_b32 v12, v130 offset:6912
	ds_read_b32 v16, v130 offset:7680
	ds_read_b32 v34, v130 offset:8448
	v_add_u32_e32 v49, s48, v54
	v_readlane_b32 s48, v255, 5
	ds_read_b32 v38, v49
	v_add_u32_e32 v234, s52, v54
	v_add_u32_e32 v232, s48, v54
	v_readlane_b32 s48, v255, 7
	ds_read_b32 v4, v234
	ds_read_b32 v36, v233
	ds_read_b32 v40, v232
	v_add_u32_e32 v48, s48, v54
	v_readlane_b32 s48, v255, 9
	s_waitcnt lgkmcnt(2)
	v_and_b32_e32 v5, 0xffff0000, v4
	s_waitcnt lgkmcnt(1)
	v_and_b32_e32 v37, 0xffff0000, v36
	v_add_u32_e32 v231, s48, v54
	v_readlane_b32 s48, v255, 11
	ds_read_b32 v44, v231
	s_waitcnt lgkmcnt(1)
	v_and_b32_e32 v41, 0xffff0000, v40
	v_add_u32_e32 v230, s48, v54
	ds_read_b32 v46, v230
	ds_read_b32 v235, v130
	ds_read_b32 v42, v48
	s_waitcnt lgkmcnt(3)
	v_and_b32_e32 v45, 0xffff0000, v44
	v_lshlrev_b32_e32 v44, 16, v44
	s_waitcnt lgkmcnt(2)
	v_and_b32_e32 v47, 0xffff0000, v46
	s_waitcnt lgkmcnt(1)
	v_and_b32_e32 v237, 0xffff0000, v235
	v_lshlrev_b32_e32 v236, 16, v235
	v_lshlrev_b32_e32 v46, 16, v46
	s_waitcnt lgkmcnt(0)
	v_and_b32_e32 v43, 0xffff0000, v42
	v_lshlrev_b32_e32 v42, 16, v42
	v_lshlrev_b32_e32 v40, 16, v40
	v_and_b32_e32 v39, 0xffff0000, v38
	v_lshlrev_b32_e32 v38, 16, v38
	s_mul_i32 s48, s34, 0x880
	v_lshlrev_b32_e32 v36, 16, v36
	v_lshlrev_b32_e32 v4, 16, v4
	v_and_b32_e32 v9, 0xffff0000, v8
	v_lshlrev_b32_e32 v8, 16, v8
	v_and_b32_e32 v13, 0xffff0000, v12
	v_lshlrev_b32_e32 v12, 16, v12
	v_and_b32_e32 v17, 0xffff0000, v16
	v_lshlrev_b32_e32 v16, 16, v16
	v_and_b32_e32 v35, 0xffff0000, v34
	v_lshlrev_b32_e32 v34, 16, v34
	s_waitcnt vmcnt(4)
	v_pk_fma_f32 v[236:237], v[2:3], v[236:237], 0 op_sel_hi:[1,1,0]
	s_waitcnt vmcnt(3)
	v_pk_fma_f32 v[236:237], v[6:7], v[46:47], v[236:237]
	v_pk_fma_f32 v[46:47], v[2:3], v[46:47], 0 op_sel_hi:[1,1,0]
	s_waitcnt vmcnt(2)
	v_pk_fma_f32 v[236:237], v[10:11], v[44:45], v[236:237]
	v_pk_fma_f32 v[46:47], v[6:7], v[44:45], v[46:47]
	s_waitcnt vmcnt(1)
	v_pk_fma_f32 v[236:237], v[14:15], v[42:43], v[236:237]
	v_pk_fma_f32 v[46:47], v[10:11], v[42:43], v[46:47]
	v_pk_fma_f32 v[44:45], v[2:3], v[44:45], 0 op_sel_hi:[1,1,0]
	v_pk_fma_f32 v[46:47], v[14:15], v[40:41], v[46:47]
	v_pk_fma_f32 v[44:45], v[6:7], v[42:43], v[44:45]
	v_pk_fma_f32 v[42:43], v[2:3], v[42:43], 0 op_sel_hi:[1,1,0]
	s_waitcnt vmcnt(0)
	v_pk_fma_f32 v[236:237], v[32:33], v[40:41], v[236:237]
	v_pk_fma_f32 v[46:47], v[32:33], v[38:39], v[46:47]
	v_mul_f32_e32 v235, 0xbfb8aa3b, v237
	v_exp_f32_e32 v235, v235
	v_pk_fma_f32 v[44:45], v[10:11], v[40:41], v[44:45]
	v_pk_fma_f32 v[42:43], v[6:7], v[40:41], v[42:43]
	v_pk_fma_f32 v[44:45], v[14:15], v[38:39], v[44:45]
	v_add_f32_e32 v235, 1.0, v235
	v_rcp_f32_e32 v239, v235
	v_mul_f32_e32 v235, 0xbfb8aa3b, v236
	v_exp_f32_e32 v235, v235
	v_pk_fma_f32 v[44:45], v[32:33], v[36:37], v[44:45]
	v_pk_fma_f32 v[42:43], v[10:11], v[38:39], v[42:43]
	v_pk_fma_f32 v[40:41], v[2:3], v[40:41], 0 op_sel_hi:[1,1,0]
	v_add_f32_e32 v235, 1.0, v235
	v_rcp_f32_e32 v238, v235
	v_pk_fma_f32 v[42:43], v[14:15], v[36:37], v[42:43]
	v_pk_fma_f32 v[40:41], v[6:7], v[38:39], v[40:41]
	v_pk_fma_f32 v[42:43], v[32:33], v[4:5], v[42:43]
	v_pk_mul_f32 v[236:237], v[236:237], v[238:239]
	v_pk_fma_f32 v[40:41], v[10:11], v[36:37], v[40:41]
	v_pk_mul_f32 v[238:239], v[236:237], v[236:237]
	v_pk_fma_f32 v[40:41], v[14:15], v[4:5], v[40:41]
	v_add_f32_e32 v235, v238, v239
	v_pk_fma_f32 v[40:41], v[32:33], v[8:9], v[40:41]
	v_pk_fma_f32 v[38:39], v[2:3], v[38:39], 0 op_sel_hi:[1,1,0]
	v_add_f32_dpp v235, v235, v235 quad_perm:[1,0,3,2] row_mask:0xf bank_mask:0xf bound_ctrl:1
	v_pk_fma_f32 v[38:39], v[6:7], v[36:37], v[38:39]
	v_pk_fma_f32 v[36:37], v[2:3], v[36:37], 0 op_sel_hi:[1,1,0]
	v_add_f32_dpp v235, v235, v235 quad_perm:[2,3,0,1] row_mask:0xf bank_mask:0xf bound_ctrl:1
	v_pk_fma_f32 v[2:3], v[2:3], v[4:5], 0 op_sel_hi:[1,1,0]
	v_pk_fma_f32 v[38:39], v[10:11], v[4:5], v[38:39]
	v_add_f32_dpp v235, v235, v235 row_half_mirror row_mask:0xf bank_mask:0xf bound_ctrl:1
	v_pk_fma_f32 v[2:3], v[6:7], v[8:9], v[2:3]
	v_pk_fma_f32 v[36:37], v[6:7], v[4:5], v[36:37]
	v_add_f32_dpp v235, v235, v235 row_mirror row_mask:0xf bank_mask:0xf bound_ctrl:1
	ds_bpermute_b32 v238, v69, v235
	v_pk_fma_f32 v[2:3], v[10:11], v[12:13], v[2:3]
	v_pk_fma_f32 v[38:39], v[14:15], v[8:9], v[38:39]
	v_pk_fma_f32 v[2:3], v[14:15], v[16:17], v[2:3]
	v_pk_fma_f32 v[38:39], v[32:33], v[12:13], v[38:39]
	s_waitcnt lgkmcnt(0)
; #define LAS __attribute__((address_space(3)))
; __device__ __forceinline__ unsigned pkbf(float a, float b) { bf16x2_t v = __builtin_convertvector((f32x2_t){a, b}, bf16x2_t); return __builtin_bit_cast(unsigned, v); }
; __device__ __forceinline__ void gdn_prep_phase(LAS unsigned char* lds, const GdnPrepArgs& A, int bid, int G, const unsigned char* zero_page) {
;     ...
;             for (int tau = 0; tau < 5; ++tau) { const f32x2_t t2 = *(const f32x2_t*)(A.conv_w + tau * 3072 + m * 1024 + h * 128 + 2 * lane); wc[tau][0] = t2.x; wc[tau][1] = t2.y; }
;             float in[12][2];
; #pragma unroll
;             for (int i = 0; i < 12; ++i) { const unsigned u = *(const LAS unsigned*)(lds + L_PRE + ((p0 + i) * 3 + m) * 256 + lane * 4); in[i][0] = bflo(u); in[i][1] = bfhi(u); }
;             float y[8][2];
; #pragma unroll
;             for (int pp = 0; pp < 8; ++pp)
; #pragma unroll
;                 for (int c = 0; c < 2; ++c) { float s = 0.f;
; #pragma unroll
;                     for (int tau = 0; tau < 5; ++tau) s += wc[tau][c] * in[pp + tau][c];
;                     y[pp][c] = s * __builtin_amdgcn_rcpf(1.0f + __builtin_amdgcn_exp2f(-1.4426950408889634f * s)); }
;             if (m < 2) {
; #pragma unroll
;                 for (int pp = 0; pp < 8; ++pp) { float ss = row16_sum(y[pp][0] * y[pp][0] + y[pp][1] * y[pp][1]); ss += __shfl_xor(ss, 16); ss += __shfl_xor(ss, 32); const float rn = __builtin_amdgcn_rsqf(ss + EPS);
;                     *(LAS unsigned*)(lds + (m == 0 ? L_QN : L_KN) + (p0 + pp) * QS_ + lane * 4) = pkbf(y[pp][0] * rn, y[pp][1] * rn); }
	v_add_f32_e32 v235, v235, v238
	ds_bpermute_b32 v238, v70, v235
	v_pk_fma_f32 v[2:3], v[32:33], v[34:35], v[2:3]
	v_pk_fma_f32 v[36:37], v[10:11], v[8:9], v[36:37]
	v_mul_f32_e32 v4, 0xbfb8aa3b, v3
	v_exp_f32_e32 v4, v4
	s_waitcnt lgkmcnt(0)
	v_add_f32_e32 v235, v235, v238
	v_add_f32_e32 v235, 0x358637bd, v235
	v_rsq_f32_e32 v238, v235
	v_add_f32_e32 v4, 1.0, v4
	v_rcp_f32_e32 v5, v4
	v_mul_f32_e32 v4, 0xbfb8aa3b, v2
	v_pk_mul_f32 v[236:237], v[236:237], v[238:239] op_sel_hi:[1,0]
	v_exp_f32_e32 v4, v4
	v_cvt_pk_bf16_f32 v235, v236, v237
	v_add_u32_e32 v236, s48, v54
	ds_write_b32 v236, v235 offset:52224
	v_mul_f32_e32 v235, 0xbfb8aa3b, v47
	v_exp_f32_e32 v235, v235
	v_add_f32_e32 v4, 1.0, v4
	v_rcp_f32_e32 v4, v4
	v_pk_fma_f32 v[36:37], v[14:15], v[12:13], v[36:37]
	v_add_f32_e32 v235, 1.0, v235
	v_rcp_f32_e32 v237, v235
	v_mul_f32_e32 v235, 0xbfb8aa3b, v46
	v_exp_f32_e32 v235, v235
	v_pk_mul_f32 v[2:3], v[2:3], v[4:5]
	v_pk_fma_f32 v[36:37], v[32:33], v[16:17], v[36:37]
	v_pk_mul_f32 v[4:5], v[2:3], v[2:3]
	v_add_f32_e32 v235, 1.0, v235
	v_rcp_f32_e32 v236, v235
	v_add_f32_e32 v4, v4, v5
	v_lshl_add_u64 v[32:33], v[28:29], 0, s[42:43]
	v_add_co_u32_e32 v6, vcc, s46, v32
	v_pk_mul_f32 v[46:47], v[46:47], v[236:237]
	v_add_f32_dpp v4, v4, v4 quad_perm:[1,0,3,2] row_mask:0xf bank_mask:0xf bound_ctrl:1
	v_pk_mul_f32 v[236:237], v[46:47], v[46:47]
	v_addc_co_u32_e32 v7, vcc, 0, v33, vcc
	v_add_f32_e32 v235, v236, v237
	v_add_f32_dpp v4, v4, v4 quad_perm:[2,3,0,1] row_mask:0xf bank_mask:0xf bound_ctrl:1
	v_add_co_u32_e32 v10, vcc, s45, v32
	v_add_f32_dpp v235, v235, v235 quad_perm:[1,0,3,2] row_mask:0xf bank_mask:0xf bound_ctrl:1
	v_add_f32_dpp v4, v4, v4 row_half_mirror row_mask:0xf bank_mask:0xf bound_ctrl:1
	v_addc_co_u32_e32 v11, vcc, 0, v33, vcc
	v_add_f32_dpp v235, v235, v235 quad_perm:[2,3,0,1] row_mask:0xf bank_mask:0xf bound_ctrl:1
	v_add_f32_dpp v4, v4, v4 row_mirror row_mask:0xf bank_mask:0xf bound_ctrl:1
	ds_bpermute_b32 v5, v69, v4
	v_add_f32_dpp v235, v235, v235 row_half_mirror row_mask:0xf bank_mask:0xf bound_ctrl:1
	v_add_co_u32_e32 v14, vcc, s47, v32
	s_nop 0
	v_add_f32_dpp v235, v235, v235 row_mirror row_mask:0xf bank_mask:0xf bound_ctrl:1
	ds_bpermute_b32 v236, v69, v235
	s_waitcnt lgkmcnt(1)
	v_add_f32_e32 v4, v4, v5
	ds_bpermute_b32 v5, v70, v4
	global_load_dwordx2 v[6:7], v[6:7], off
	v_addc_co_u32_e32 v15, vcc, 0, v33, vcc
	s_waitcnt lgkmcnt(1)
	v_add_f32_e32 v235, v235, v236
	ds_bpermute_b32 v236, v70, v235
	s_waitcnt lgkmcnt(1)
	v_add_f32_e32 v4, v4, v5
	v_add_f32_e32 v4, 0x358637bd, v4
	v_rsq_f32_e32 v4, v4
	global_load_dwordx2 v[10:11], v[10:11], off
	s_waitcnt lgkmcnt(0)
	v_add_f32_e32 v235, v235, v236
	v_add_f32_e32 v235, 0x358637bd, v235
	v_rsq_f32_e32 v236, v235
	v_mul_f32_e32 v235, 0xbfb8aa3b, v45
	v_exp_f32_e32 v235, v235
	v_pk_mul_f32 v[2:3], v[2:3], v[4:5] op_sel_hi:[1,0]
	v_pk_mul_f32 v[46:47], v[46:47], v[236:237] op_sel_hi:[1,0]
	v_cvt_pk_bf16_f32 v2, v2, v3
	v_add_f32_e32 v235, 1.0, v235
	v_rcp_f32_e32 v237, v235
	v_mul_f32_e32 v235, 0xbfb8aa3b, v44
	v_exp_f32_e32 v235, v235
	v_cvt_pk_bf16_f32 v47, v46, v47
	v_add_u32_e32 v46, s53, v54
	ds_write_b32 v46, v2 offset:53856
	v_add_f32_e32 v235, 1.0, v235
	v_rcp_f32_e32 v236, v235
	global_load_dwordx2 v[2:3], v[32:33], off
	ds_read_b32 v8, v130 offset:6400
	ds_read_b32 v12, v130 offset:7168
	ds_read_b32 v16, v130 offset:7936
	ds_read_b32 v34, v130 offset:8704
	v_pk_mul_f32 v[44:45], v[44:45], v[236:237]
	global_load_dwordx2 v[14:15], v[14:15], off
	v_pk_mul_f32 v[236:237], v[44:45], v[44:45]
	v_add_co_u32_e32 v32, vcc, s44, v32
	v_add_f32_e32 v235, v236, v237
	s_nop 0
	v_addc_co_u32_e32 v33, vcc, 0, v33, vcc
	v_add_f32_dpp v235, v235, v235 quad_perm:[1,0,3,2] row_mask:0xf bank_mask:0xf bound_ctrl:1
	global_load_dwordx2 v[32:33], v[32:33], off
	ds_read_b32 v4, v234 offset:256
	v_add_f32_dpp v235, v235, v235 quad_perm:[2,3,0,1] row_mask:0xf bank_mask:0xf bound_ctrl:1
	s_nop 1
	v_add_f32_dpp v235, v235, v235 row_half_mirror row_mask:0xf bank_mask:0xf bound_ctrl:1
	s_nop 1
	v_add_f32_dpp v235, v235, v235 row_mirror row_mask:0xf bank_mask:0xf bound_ctrl:1
	ds_bpermute_b32 v236, v69, v235
	s_waitcnt lgkmcnt(0)
	v_add_f32_e32 v235, v235, v236
	ds_bpermute_b32 v236, v70, v235
	s_waitcnt lgkmcnt(0)
	v_add_f32_e32 v235, v235, v236
	v_add_f32_e32 v235, 0x358637bd, v235
	v_rsq_f32_e32 v236, v235
	v_add_u32_e32 v235, 0xcc00, v46
	v_pk_mul_f32 v[44:45], v[44:45], v[236:237] op_sel_hi:[1,0]
	s_nop 0
	v_cvt_pk_bf16_f32 v44, v44, v45
	ds_write2_b32 v235, v47, v44 offset1:68
	v_mul_f32_e32 v44, 0xbfb8aa3b, v43
	v_exp_f32_e32 v44, v44
	s_nop 0
	v_add_f32_e32 v44, 1.0, v44
	v_rcp_f32_e32 v45, v44
	v_mul_f32_e32 v44, 0xbfb8aa3b, v42
	v_exp_f32_e32 v44, v44
	s_nop 0
	v_add_f32_e32 v44, 1.0, v44
	v_rcp_f32_e32 v44, v44
	s_nop 0
	v_pk_mul_f32 v[42:43], v[42:43], v[44:45]
	s_nop 0
	v_pk_mul_f32 v[44:45], v[42:43], v[42:43]
	s_nop 0
	v_add_f32_e32 v44, v44, v45
	s_nop 1
	v_add_f32_dpp v44, v44, v44 quad_perm:[1,0,3,2] row_mask:0xf bank_mask:0xf bound_ctrl:1
	s_nop 1
	v_add_f32_dpp v44, v44, v44 quad_perm:[2,3,0,1] row_mask:0xf bank_mask:0xf bound_ctrl:1
	s_nop 1
	v_add_f32_dpp v44, v44, v44 row_half_mirror row_mask:0xf bank_mask:0xf bound_ctrl:1
	s_nop 1
	v_add_f32_dpp v44, v44, v44 row_mirror row_mask:0xf bank_mask:0xf bound_ctrl:1
	ds_bpermute_b32 v45, v69, v44
	s_waitcnt lgkmcnt(0)
	v_add_f32_e32 v44, v44, v45
	ds_bpermute_b32 v45, v70, v44
	s_waitcnt lgkmcnt(0)
; #define LAS __attribute__((address_space(3)))
; __device__ __forceinline__ unsigned pkbf(float a, float b) { bf16x2_t v = __builtin_convertvector((f32x2_t){a, b}, bf16x2_t); return __builtin_bit_cast(unsigned, v); }
; __device__ __forceinline__ void gdn_prep_phase(LAS unsigned char* lds, const GdnPrepArgs& A, int bid, int G, const unsigned char* zero_page) {
;     ...
;             for (int i = 0; i < 12; ++i) { const unsigned u = *(const LAS unsigned*)(lds + L_PRE + ((p0 + i) * 3 + m) * 256 + lane * 4); in[i][0] = bflo(u); in[i][1] = bfhi(u); }
;             float y[8][2];
; #pragma unroll
;             for (int pp = 0; pp < 8; ++pp)
; #pragma unroll
;                 for (int c = 0; c < 2; ++c) { float s = 0.f;
; #pragma unroll
;                     for (int tau = 0; tau < 5; ++tau) s += wc[tau][c] * in[pp + tau][c];
;                     y[pp][c] = s * __builtin_amdgcn_rcpf(1.0f + __builtin_amdgcn_exp2f(-1.4426950408889634f * s)); }
;             if (m < 2) {
; #pragma unroll
;                 for (int pp = 0; pp < 8; ++pp) { float ss = row16_sum(y[pp][0] * y[pp][0] + y[pp][1] * y[pp][1]); ss += __shfl_xor(ss, 16); ss += __shfl_xor(ss, 32); const float rn = __builtin_amdgcn_rsqf(ss + EPS);
;                     *(LAS unsigned*)(lds + (m == 0 ? L_QN : L_KN) + (p0 + pp) * QS_ + lane * 4) = pkbf(y[pp][0] * rn, y[pp][1] * rn); }
	v_add_f32_e32 v44, v44, v45
	v_add_f32_e32 v44, 0x358637bd, v44
	v_rsq_f32_e32 v44, v44
	s_nop 0
	v_pk_mul_f32 v[42:43], v[42:43], v[44:45] op_sel_hi:[1,0]
	s_nop 0
	v_cvt_pk_bf16_f32 v44, v42, v43
	v_mul_f32_e32 v42, 0xbfb8aa3b, v41
	v_exp_f32_e32 v42, v42
	s_nop 0
	v_add_f32_e32 v42, 1.0, v42
	v_rcp_f32_e32 v43, v42
	v_mul_f32_e32 v42, 0xbfb8aa3b, v40
	v_exp_f32_e32 v42, v42
	s_nop 0
	v_add_f32_e32 v42, 1.0, v42
	v_rcp_f32_e32 v42, v42
	s_nop 0
	v_pk_mul_f32 v[40:41], v[40:41], v[42:43]
	s_nop 0
	v_pk_mul_f32 v[42:43], v[40:41], v[40:41]
	s_nop 0
	v_add_f32_e32 v42, v42, v43
	s_nop 1
	v_add_f32_dpp v42, v42, v42 quad_perm:[1,0,3,2] row_mask:0xf bank_mask:0xf bound_ctrl:1
	s_nop 1
	v_add_f32_dpp v42, v42, v42 quad_perm:[2,3,0,1] row_mask:0xf bank_mask:0xf bound_ctrl:1
	s_nop 1
	v_add_f32_dpp v42, v42, v42 row_half_mirror row_mask:0xf bank_mask:0xf bound_ctrl:1
	s_nop 1
	v_add_f32_dpp v42, v42, v42 row_mirror row_mask:0xf bank_mask:0xf bound_ctrl:1
	ds_bpermute_b32 v43, v69, v42
	s_waitcnt lgkmcnt(0)
	v_add_f32_e32 v42, v42, v43
	ds_bpermute_b32 v43, v70, v42
	s_waitcnt lgkmcnt(0)
	v_add_f32_e32 v42, v42, v43
	v_add_f32_e32 v42, 0x358637bd, v42
	v_rsq_f32_e32 v42, v42
	s_nop 0
	v_pk_mul_f32 v[40:41], v[40:41], v[42:43] op_sel_hi:[1,0]
	s_nop 0
	v_cvt_pk_bf16_f32 v40, v40, v41
	ds_write2_b32 v235, v44, v40 offset0:136 offset1:204
	v_mul_f32_e32 v40, 0xbfb8aa3b, v39
	v_exp_f32_e32 v40, v40
	ds_read_b32 v44, v231 offset:256
	v_add_f32_e32 v40, 1.0, v40
	v_rcp_f32_e32 v41, v40
	v_mul_f32_e32 v40, 0xbfb8aa3b, v38
	v_exp_f32_e32 v40, v40
	s_waitcnt lgkmcnt(0)
	v_and_b32_e32 v45, 0xffff0000, v44
	v_lshlrev_b32_e32 v44, 16, v44
	v_add_f32_e32 v40, 1.0, v40
	v_rcp_f32_e32 v40, v40
	s_nop 0
	v_pk_mul_f32 v[38:39], v[38:39], v[40:41]
	s_nop 0
	v_pk_mul_f32 v[40:41], v[38:39], v[38:39]
	s_nop 0
	v_add_f32_e32 v40, v40, v41
	s_nop 1
	v_add_f32_dpp v40, v40, v40 quad_perm:[1,0,3,2] row_mask:0xf bank_mask:0xf bound_ctrl:1
	s_nop 1
	v_add_f32_dpp v40, v40, v40 quad_perm:[2,3,0,1] row_mask:0xf bank_mask:0xf bound_ctrl:1
	s_nop 1
	v_add_f32_dpp v40, v40, v40 row_half_mirror row_mask:0xf bank_mask:0xf bound_ctrl:1
	s_nop 1
	v_add_f32_dpp v40, v40, v40 row_mirror row_mask:0xf bank_mask:0xf bound_ctrl:1
	ds_bpermute_b32 v41, v69, v40
	s_waitcnt lgkmcnt(0)
	v_add_f32_e32 v40, v40, v41
	ds_bpermute_b32 v41, v70, v40
	s_waitcnt lgkmcnt(0)
	v_add_f32_e32 v40, v40, v41
	v_add_f32_e32 v40, 0x358637bd, v40
	v_rsq_f32_e32 v40, v40
	s_nop 0
	v_pk_mul_f32 v[38:39], v[38:39], v[40:41] op_sel_hi:[1,0]
	s_nop 0
	v_cvt_pk_bf16_f32 v40, v38, v39
	v_mul_f32_e32 v38, 0xbfb8aa3b, v37
	v_exp_f32_e32 v38, v38
	s_nop 0
	v_add_f32_e32 v38, 1.0, v38
	v_rcp_f32_e32 v39, v38
	v_mul_f32_e32 v38, 0xbfb8aa3b, v36
	v_exp_f32_e32 v38, v38
	s_nop 0
	v_add_f32_e32 v38, 1.0, v38
	v_rcp_f32_e32 v38, v38
	s_nop 0
	v_pk_mul_f32 v[36:37], v[36:37], v[38:39]
	s_nop 0
	v_pk_mul_f32 v[38:39], v[36:37], v[36:37]
	s_nop 0
	v_add_f32_e32 v38, v38, v39
	s_nop 1
	v_add_f32_dpp v38, v38, v38 quad_perm:[1,0,3,2] row_mask:0xf bank_mask:0xf bound_ctrl:1
	s_nop 1
	v_add_f32_dpp v38, v38, v38 quad_perm:[2,3,0,1] row_mask:0xf bank_mask:0xf bound_ctrl:1
	s_nop 1
	v_add_f32_dpp v38, v38, v38 row_half_mirror row_mask:0xf bank_mask:0xf bound_ctrl:1
	s_nop 1
	v_add_f32_dpp v38, v38, v38 row_mirror row_mask:0xf bank_mask:0xf bound_ctrl:1
	ds_bpermute_b32 v39, v69, v38
	s_waitcnt lgkmcnt(0)
	v_add_f32_e32 v38, v38, v39
	ds_bpermute_b32 v39, v70, v38
	s_waitcnt lgkmcnt(0)
	v_add_f32_e32 v38, v38, v39
	v_add_f32_e32 v38, 0x358637bd, v38
	v_rsq_f32_e32 v38, v38
	s_nop 0
	v_pk_mul_f32 v[36:37], v[36:37], v[38:39] op_sel_hi:[1,0]
	s_nop 0
	v_cvt_pk_bf16_f32 v36, v36, v37
	v_add_u32_e32 v37, 0xd000, v46
	ds_write2_b32 v37, v40, v36 offset0:16 offset1:84
	ds_read_b32 v38, v49 offset:256
	ds_read_b32 v46, v230 offset:256
	ds_read_b32 v235, v130 offset:256
	ds_read_b32 v42, v48 offset:256
	ds_read_b32 v36, v233 offset:256
	ds_read_b32 v40, v232 offset:256
	s_waitcnt lgkmcnt(4)
	v_and_b32_e32 v47, 0xffff0000, v46
	s_waitcnt lgkmcnt(3)
	v_and_b32_e32 v237, 0xffff0000, v235
	v_lshlrev_b32_e32 v236, 16, v235
	v_lshlrev_b32_e32 v46, 16, v46
	s_waitcnt vmcnt(2)
	v_pk_fma_f32 v[236:237], v[2:3], v[236:237], 0 op_sel_hi:[1,1,0]
	s_waitcnt lgkmcnt(2)
	v_and_b32_e32 v43, 0xffff0000, v42
	v_pk_fma_f32 v[236:237], v[6:7], v[46:47], v[236:237]
	v_lshlrev_b32_e32 v42, 16, v42
	v_pk_fma_f32 v[236:237], v[10:11], v[44:45], v[236:237]
	s_waitcnt lgkmcnt(0)
	v_and_b32_e32 v41, 0xffff0000, v40
	v_lshlrev_b32_e32 v40, 16, v40
	s_waitcnt vmcnt(1)
	v_pk_fma_f32 v[236:237], v[14:15], v[42:43], v[236:237]
	v_pk_fma_f32 v[46:47], v[2:3], v[46:47], 0 op_sel_hi:[1,1,0]
	s_waitcnt vmcnt(0)
; #define LAS __attribute__((address_space(3)))
; __device__ __forceinline__ unsigned pkbf(float a, float b) { bf16x2_t v = __builtin_convertvector((f32x2_t){a, b}, bf16x2_t); return __builtin_bit_cast(unsigned, v); }
; __device__ __forceinline__ void gdn_prep_phase(LAS unsigned char* lds, const GdnPrepArgs& A, int bid, int G, const unsigned char* zero_page) {
;     ...
;             for (int tau = 0; tau < 5; ++tau) { const f32x2_t t2 = *(const f32x2_t*)(A.conv_w + tau * 3072 + m * 1024 + h * 128 + 2 * lane); wc[tau][0] = t2.x; wc[tau][1] = t2.y; }
;             float in[12][2];
; #pragma unroll
;             for (int i = 0; i < 12; ++i) { const unsigned u = *(const LAS unsigned*)(lds + L_PRE + ((p0 + i) * 3 + m) * 256 + lane * 4); in[i][0] = bflo(u); in[i][1] = bfhi(u); }
;             float y[8][2];
; #pragma unroll
;             for (int pp = 0; pp < 8; ++pp)
; #pragma unroll
;                 for (int c = 0; c < 2; ++c) { float s = 0.f;
; #pragma unroll
;                     for (int tau = 0; tau < 5; ++tau) s += wc[tau][c] * in[pp + tau][c];
;                     y[pp][c] = s * __builtin_amdgcn_rcpf(1.0f + __builtin_amdgcn_exp2f(-1.4426950408889634f * s)); }
;             if (m < 2) {
; #pragma unroll
;                 for (int pp = 0; pp < 8; ++pp) { float ss = row16_sum(y[pp][0] * y[pp][0] + y[pp][1] * y[pp][1]); ss += __shfl_xor(ss, 16); ss += __shfl_xor(ss, 32); const float rn = __builtin_amdgcn_rsqf(ss + EPS);
;                     *(LAS unsigned*)(lds + (m == 0 ? L_QN : L_KN) + (p0 + pp) * QS_ + lane * 4) = pkbf(y[pp][0] * rn, y[pp][1] * rn); }
	v_pk_fma_f32 v[236:237], v[32:33], v[40:41], v[236:237]
	v_pk_fma_f32 v[46:47], v[6:7], v[44:45], v[46:47]
	v_mul_f32_e32 v235, 0xbfb8aa3b, v237
	v_exp_f32_e32 v235, v235
	v_pk_fma_f32 v[46:47], v[10:11], v[42:43], v[46:47]
	v_and_b32_e32 v39, 0xffff0000, v38
	v_lshlrev_b32_e32 v38, 16, v38
	v_add_f32_e32 v235, 1.0, v235
	v_rcp_f32_e32 v239, v235
	v_mul_f32_e32 v235, 0xbfb8aa3b, v236
	v_exp_f32_e32 v235, v235
	v_pk_fma_f32 v[46:47], v[14:15], v[40:41], v[46:47]
	v_pk_fma_f32 v[44:45], v[2:3], v[44:45], 0 op_sel_hi:[1,1,0]
	v_pk_fma_f32 v[46:47], v[32:33], v[38:39], v[46:47]
	v_add_f32_e32 v235, 1.0, v235
	v_rcp_f32_e32 v238, v235
	v_pk_fma_f32 v[44:45], v[6:7], v[42:43], v[44:45]
	v_and_b32_e32 v37, 0xffff0000, v36
	v_pk_fma_f32 v[44:45], v[10:11], v[40:41], v[44:45]
	v_pk_mul_f32 v[236:237], v[236:237], v[238:239]
	v_lshlrev_b32_e32 v36, 16, v36
	v_pk_mul_f32 v[238:239], v[236:237], v[236:237]
	v_pk_fma_f32 v[44:45], v[14:15], v[38:39], v[44:45]
	v_add_f32_e32 v235, v238, v239
	v_pk_fma_f32 v[44:45], v[32:33], v[36:37], v[44:45]
	v_pk_fma_f32 v[42:43], v[2:3], v[42:43], 0 op_sel_hi:[1,1,0]
	v_add_f32_dpp v235, v235, v235 quad_perm:[1,0,3,2] row_mask:0xf bank_mask:0xf bound_ctrl:1
	v_pk_fma_f32 v[42:43], v[6:7], v[40:41], v[42:43]
	v_and_b32_e32 v5, 0xffff0000, v4
	v_add_f32_dpp v235, v235, v235 quad_perm:[2,3,0,1] row_mask:0xf bank_mask:0xf bound_ctrl:1
	v_pk_fma_f32 v[42:43], v[10:11], v[38:39], v[42:43]
	v_lshlrev_b32_e32 v4, 16, v4
	v_add_f32_dpp v235, v235, v235 row_half_mirror row_mask:0xf bank_mask:0xf bound_ctrl:1
	v_pk_fma_f32 v[42:43], v[14:15], v[36:37], v[42:43]
	v_pk_fma_f32 v[40:41], v[2:3], v[40:41], 0 op_sel_hi:[1,1,0]
	v_add_f32_dpp v235, v235, v235 row_mirror row_mask:0xf bank_mask:0xf bound_ctrl:1
	ds_bpermute_b32 v238, v69, v235
	v_pk_fma_f32 v[42:43], v[32:33], v[4:5], v[42:43]
	v_pk_fma_f32 v[40:41], v[6:7], v[38:39], v[40:41]
	v_and_b32_e32 v9, 0xffff0000, v8
	v_pk_fma_f32 v[40:41], v[10:11], v[36:37], v[40:41]
	s_waitcnt lgkmcnt(0)
	v_add_f32_e32 v235, v235, v238
	ds_bpermute_b32 v238, v70, v235
	v_lshlrev_b32_e32 v8, 16, v8
	v_pk_fma_f32 v[40:41], v[14:15], v[4:5], v[40:41]
	v_pk_fma_f32 v[38:39], v[2:3], v[38:39], 0 op_sel_hi:[1,1,0]
	v_pk_fma_f32 v[40:41], v[32:33], v[8:9], v[40:41]
	s_waitcnt lgkmcnt(0)
	v_add_f32_e32 v235, v235, v238
	v_add_f32_e32 v235, 0x358637bd, v235
	v_rsq_f32_e32 v238, v235
	v_pk_fma_f32 v[38:39], v[6:7], v[36:37], v[38:39]
	v_pk_fma_f32 v[36:37], v[2:3], v[36:37], 0 op_sel_hi:[1,1,0]
	v_pk_fma_f32 v[2:3], v[2:3], v[4:5], 0 op_sel_hi:[1,1,0]
	v_pk_mul_f32 v[236:237], v[236:237], v[238:239] op_sel_hi:[1,0]
	v_and_b32_e32 v13, 0xffff0000, v12
	v_cvt_pk_bf16_f32 v235, v236, v237
	v_add_u32_e32 v236, s48, v71
	ds_write_b32 v236, v235
	v_mul_f32_e32 v235, 0xbfb8aa3b, v47
	v_exp_f32_e32 v235, v235
	v_lshlrev_b32_e32 v12, 16, v12
	v_pk_fma_f32 v[2:3], v[6:7], v[8:9], v[2:3]
	v_and_b32_e32 v17, 0xffff0000, v16
	v_add_f32_e32 v235, 1.0, v235
	v_rcp_f32_e32 v237, v235
	v_mul_f32_e32 v235, 0xbfb8aa3b, v46
	v_exp_f32_e32 v235, v235
	v_lshlrev_b32_e32 v16, 16, v16
	v_pk_fma_f32 v[2:3], v[10:11], v[12:13], v[2:3]
	v_and_b32_e32 v35, 0xffff0000, v34
	v_add_f32_e32 v235, 1.0, v235
	v_rcp_f32_e32 v236, v235
	v_lshlrev_b32_e32 v34, 16, v34
	v_pk_fma_f32 v[2:3], v[14:15], v[16:17], v[2:3]
	v_pk_fma_f32 v[38:39], v[10:11], v[4:5], v[38:39]
	v_pk_mul_f32 v[46:47], v[46:47], v[236:237]
	v_pk_fma_f32 v[2:3], v[32:33], v[34:35], v[2:3]
	v_pk_mul_f32 v[236:237], v[46:47], v[46:47]
	v_pk_fma_f32 v[36:37], v[6:7], v[4:5], v[36:37]
	v_add_f32_e32 v235, v236, v237
	v_mul_f32_e32 v4, 0xbfb8aa3b, v3
	v_exp_f32_e32 v4, v4
	v_add_f32_dpp v235, v235, v235 quad_perm:[1,0,3,2] row_mask:0xf bank_mask:0xf bound_ctrl:1
	v_pk_fma_f32 v[38:39], v[14:15], v[8:9], v[38:39]
	v_pk_fma_f32 v[36:37], v[10:11], v[8:9], v[36:37]
	v_add_f32_dpp v235, v235, v235 quad_perm:[2,3,0,1] row_mask:0xf bank_mask:0xf bound_ctrl:1
	v_add_f32_e32 v4, 1.0, v4
	v_rcp_f32_e32 v5, v4
	v_add_f32_dpp v235, v235, v235 row_half_mirror row_mask:0xf bank_mask:0xf bound_ctrl:1
	v_mul_f32_e32 v4, 0xbfb8aa3b, v2
	v_exp_f32_e32 v4, v4
	v_add_f32_dpp v235, v235, v235 row_mirror row_mask:0xf bank_mask:0xf bound_ctrl:1
	ds_bpermute_b32 v236, v69, v235
	v_pk_fma_f32 v[38:39], v[32:33], v[12:13], v[38:39]
	v_add_f32_e32 v4, 1.0, v4
	v_rcp_f32_e32 v4, v4
	v_lshl_add_u64 v[10:11], v[30:31], 0, s[42:43]
	s_waitcnt lgkmcnt(0)
	v_add_f32_e32 v235, v235, v236
	ds_bpermute_b32 v236, v70, v235
	v_pk_mul_f32 v[2:3], v[2:3], v[4:5]
	v_pk_fma_f32 v[36:37], v[14:15], v[12:13], v[36:37]
	v_pk_mul_f32 v[4:5], v[2:3], v[2:3]
	v_pk_fma_f32 v[36:37], v[32:33], v[16:17], v[36:37]
	s_waitcnt lgkmcnt(0)
	v_add_f32_e32 v235, v235, v236
	v_add_f32_e32 v235, 0x358637bd, v235
	v_rsq_f32_e32 v236, v235
	v_add_f32_e32 v4, v4, v5
	ds_read_b32 v14, v234 offset:512
	ds_read_b32 v15, v130 offset:6656
	ds_read_b32 v16, v130 offset:7424
	ds_read_b32 v17, v130 offset:8192
	v_pk_mul_f32 v[46:47], v[46:47], v[236:237] op_sel_hi:[1,0]
	v_add_u32_e32 v236, s53, v71
	v_cvt_pk_bf16_f32 v235, v46, v47
	v_mul_f32_e32 v46, 0xbfb8aa3b, v45
	v_exp_f32_e32 v46, v46
	v_add_f32_dpp v4, v4, v4 quad_perm:[1,0,3,2] row_mask:0xf bank_mask:0xf bound_ctrl:1
	s_waitcnt lgkmcnt(3)
	v_and_b32_e32 v32, 0xffff0000, v14
	v_mov_b32_e32 v35, v32
	v_add_f32_e32 v46, 1.0, v46
	v_rcp_f32_e32 v47, v46
	v_mul_f32_e32 v46, 0xbfb8aa3b, v44
	v_exp_f32_e32 v46, v46
	v_add_f32_dpp v4, v4, v4 quad_perm:[2,3,0,1] row_mask:0xf bank_mask:0xf bound_ctrl:1
	s_waitcnt lgkmcnt(2)
	v_and_b32_e32 v33, 0xffff0000, v15
	s_waitcnt lgkmcnt(0)
; #define LAS __attribute__((address_space(3)))
; __device__ __forceinline__ unsigned pkbf(float a, float b) { bf16x2_t v = __builtin_convertvector((f32x2_t){a, b}, bf16x2_t); return __builtin_bit_cast(unsigned, v); }
; __device__ __forceinline__ void gdn_prep_phase(LAS unsigned char* lds, const GdnPrepArgs& A, int bid, int G, const unsigned char* zero_page) {
;     ...
;             for (int tau = 0; tau < 5; ++tau) { const f32x2_t t2 = *(const f32x2_t*)(A.conv_w + tau * 3072 + m * 1024 + h * 128 + 2 * lane); wc[tau][0] = t2.x; wc[tau][1] = t2.y; }
;             float in[12][2];
; #pragma unroll
;             for (int i = 0; i < 12; ++i) { const unsigned u = *(const LAS unsigned*)(lds + L_PRE + ((p0 + i) * 3 + m) * 256 + lane * 4); in[i][0] = bflo(u); in[i][1] = bfhi(u); }
;             float y[8][2];
; #pragma unroll
;             for (int pp = 0; pp < 8; ++pp)
; #pragma unroll
;                 for (int c = 0; c < 2; ++c) { float s = 0.f;
; #pragma unroll
;                     for (int tau = 0; tau < 5; ++tau) s += wc[tau][c] * in[pp + tau][c];
;                     y[pp][c] = s * __builtin_amdgcn_rcpf(1.0f + __builtin_amdgcn_exp2f(-1.4426950408889634f * s)); }
;             if (m < 2) {
; #pragma unroll
;                 for (int pp = 0; pp < 8; ++pp) { float ss = row16_sum(y[pp][0] * y[pp][0] + y[pp][1] * y[pp][1]); ss += __shfl_xor(ss, 16); ss += __shfl_xor(ss, 32); const float rn = __builtin_amdgcn_rsqf(ss + EPS);
;                     *(LAS unsigned*)(lds + (m == 0 ? L_QN : L_KN) + (p0 + pp) * QS_ + lane * 4) = pkbf(y[pp][0] * rn, y[pp][1] * rn); }
	v_and_b32_e32 v13, 0xffff0000, v17
	v_add_f32_e32 v46, 1.0, v46
	v_rcp_f32_e32 v46, v46
	v_add_f32_dpp v4, v4, v4 row_half_mirror row_mask:0xf bank_mask:0xf bound_ctrl:1
	s_mov_b64 s[42:43], 0x14800
	v_pk_mul_f32 v[44:45], v[44:45], v[46:47]
	s_nop 0
	v_pk_mul_f32 v[46:47], v[44:45], v[44:45]
	v_add_f32_dpp v4, v4, v4 row_mirror row_mask:0xf bank_mask:0xf bound_ctrl:1
	v_add_f32_e32 v46, v46, v47
	ds_bpermute_b32 v5, v69, v4
	s_waitcnt lgkmcnt(0)
	v_add_f32_e32 v4, v4, v5
	v_add_f32_dpp v46, v46, v46 quad_perm:[1,0,3,2] row_mask:0xf bank_mask:0xf bound_ctrl:1
	ds_bpermute_b32 v5, v70, v4
	s_waitcnt lgkmcnt(0)
	v_add_f32_e32 v4, v4, v5
	v_add_f32_dpp v46, v46, v46 quad_perm:[2,3,0,1] row_mask:0xf bank_mask:0xf bound_ctrl:1
	v_add_f32_e32 v4, 0x358637bd, v4
	v_rsq_f32_e32 v4, v4
	v_add_f32_dpp v46, v46, v46 row_half_mirror row_mask:0xf bank_mask:0xf bound_ctrl:1
	v_pk_mul_f32 v[2:3], v[2:3], v[4:5] op_sel_hi:[1,0]
	s_nop 0
	v_add_f32_dpp v46, v46, v46 row_mirror row_mask:0xf bank_mask:0xf bound_ctrl:1
	ds_bpermute_b32 v47, v69, v46
	v_add_co_u32_e32 v4, vcc, s46, v10
	v_cvt_pk_bf16_f32 v2, v2, v3
	s_nop 0
	v_addc_co_u32_e32 v5, vcc, 0, v11, vcc
	s_waitcnt lgkmcnt(0)
	v_add_f32_e32 v46, v46, v47
	ds_bpermute_b32 v47, v70, v46
	v_add_co_u32_e32 v6, vcc, s45, v10
	ds_write_b32 v236, v2 offset:1632
	s_nop 0
	v_addc_co_u32_e32 v7, vcc, 0, v11, vcc
	s_waitcnt lgkmcnt(1)
	v_add_f32_e32 v46, v46, v47
	v_add_f32_e32 v46, 0x358637bd, v46
	v_rsq_f32_e32 v46, v46
	global_load_dwordx2 v[2:3], v[10:11], off
	v_add_co_u32_e32 v8, vcc, s47, v10
	v_pk_mul_f32 v[44:45], v[44:45], v[46:47] op_sel_hi:[1,0]
	global_load_dwordx2 v[4:5], v[4:5], off
	v_cvt_pk_bf16_f32 v44, v44, v45
	ds_write2_b32 v236, v235, v44 offset1:68
	v_mul_f32_e32 v44, 0xbfb8aa3b, v43
	v_exp_f32_e32 v44, v44
	v_addc_co_u32_e32 v9, vcc, 0, v11, vcc
	global_load_dwordx2 v[6:7], v[6:7], off
	v_add_f32_e32 v44, 1.0, v44
	v_rcp_f32_e32 v45, v44
	v_mul_f32_e32 v44, 0xbfb8aa3b, v42
	v_exp_f32_e32 v44, v44
	global_load_dwordx2 v[8:9], v[8:9], off
	v_add_co_u32_e32 v10, vcc, s44, v10
	v_add_f32_e32 v44, 1.0, v44
	v_rcp_f32_e32 v44, v44
	v_addc_co_u32_e32 v11, vcc, 0, v11, vcc
	global_load_dwordx2 v[10:11], v[10:11], off
	v_pk_mul_f32 v[42:43], v[42:43], v[44:45]
	s_nop 0
	v_pk_mul_f32 v[44:45], v[42:43], v[42:43]
	s_nop 0
	v_add_f32_e32 v44, v44, v45
	s_nop 1
	v_add_f32_dpp v44, v44, v44 quad_perm:[1,0,3,2] row_mask:0xf bank_mask:0xf bound_ctrl:1
	s_nop 1
	v_add_f32_dpp v44, v44, v44 quad_perm:[2,3,0,1] row_mask:0xf bank_mask:0xf bound_ctrl:1
	s_nop 1
	v_add_f32_dpp v44, v44, v44 row_half_mirror row_mask:0xf bank_mask:0xf bound_ctrl:1
	s_nop 1
	v_add_f32_dpp v44, v44, v44 row_mirror row_mask:0xf bank_mask:0xf bound_ctrl:1
	ds_bpermute_b32 v45, v69, v44
	s_waitcnt lgkmcnt(0)
	v_add_f32_e32 v44, v44, v45
	ds_bpermute_b32 v45, v70, v44
	s_waitcnt lgkmcnt(0)
	v_add_f32_e32 v44, v44, v45
	v_add_f32_e32 v44, 0x358637bd, v44
	v_rsq_f32_e32 v44, v44
	s_nop 0
	v_pk_mul_f32 v[42:43], v[42:43], v[44:45] op_sel_hi:[1,0]
	s_nop 0
	v_cvt_pk_bf16_f32 v44, v42, v43
	v_mul_f32_e32 v42, 0xbfb8aa3b, v41
	v_exp_f32_e32 v42, v42
	v_lshlrev_b32_e32 v45, 16, v16
	v_add_f32_e32 v42, 1.0, v42
	v_rcp_f32_e32 v43, v42
	v_mul_f32_e32 v42, 0xbfb8aa3b, v40
	v_exp_f32_e32 v42, v42
	s_nop 0
	v_add_f32_e32 v42, 1.0, v42
	v_rcp_f32_e32 v42, v42
	s_nop 0
	v_pk_mul_f32 v[40:41], v[40:41], v[42:43]
	s_nop 0
	v_pk_mul_f32 v[42:43], v[40:41], v[40:41]
	s_nop 0
	v_add_f32_e32 v42, v42, v43
	s_nop 1
	v_add_f32_dpp v42, v42, v42 quad_perm:[1,0,3,2] row_mask:0xf bank_mask:0xf bound_ctrl:1
	s_nop 1
	v_add_f32_dpp v42, v42, v42 quad_perm:[2,3,0,1] row_mask:0xf bank_mask:0xf bound_ctrl:1
	s_nop 1
	v_add_f32_dpp v42, v42, v42 row_half_mirror row_mask:0xf bank_mask:0xf bound_ctrl:1
	s_nop 1
	v_add_f32_dpp v42, v42, v42 row_mirror row_mask:0xf bank_mask:0xf bound_ctrl:1
	ds_bpermute_b32 v43, v69, v42
	s_waitcnt lgkmcnt(0)
	v_add_f32_e32 v42, v42, v43
	ds_bpermute_b32 v43, v70, v42
	s_waitcnt lgkmcnt(0)
	v_add_f32_e32 v42, v42, v43
	v_add_f32_e32 v42, 0x358637bd, v42
	v_rsq_f32_e32 v42, v42
	s_nop 0
	v_pk_mul_f32 v[40:41], v[40:41], v[42:43] op_sel_hi:[1,0]
	s_nop 0
	v_cvt_pk_bf16_f32 v40, v40, v41
	ds_write2_b32 v236, v44, v40 offset0:136 offset1:204
	v_mul_f32_e32 v40, 0xbfb8aa3b, v39
	v_exp_f32_e32 v40, v40
	v_lshlrev_b32_e32 v42, 16, v14
	v_lshlrev_b32_e32 v43, 16, v15
	v_mov_b32_e32 v44, v43
	v_add_f32_e32 v40, 1.0, v40
	v_rcp_f32_e32 v41, v40
	v_mul_f32_e32 v40, 0xbfb8aa3b, v38
	v_exp_f32_e32 v40, v40
	v_lshlrev_b32_e32 v15, 16, v17
	v_mov_b32_e32 v14, v45
	v_add_f32_e32 v40, 1.0, v40
	v_rcp_f32_e32 v40, v40
	s_nop 0
	v_pk_mul_f32 v[38:39], v[38:39], v[40:41]
	s_nop 0
	v_pk_mul_f32 v[40:41], v[38:39], v[38:39]
	s_nop 0
	v_add_f32_e32 v40, v40, v41
	s_nop 1
	v_add_f32_dpp v40, v40, v40 quad_perm:[1,0,3,2] row_mask:0xf bank_mask:0xf bound_ctrl:1
	s_nop 1
	v_add_f32_dpp v40, v40, v40 quad_perm:[2,3,0,1] row_mask:0xf bank_mask:0xf bound_ctrl:1
	s_nop 1
	v_add_f32_dpp v40, v40, v40 row_half_mirror row_mask:0xf bank_mask:0xf bound_ctrl:1
	s_nop 1
	v_add_f32_dpp v40, v40, v40 row_mirror row_mask:0xf bank_mask:0xf bound_ctrl:1
	ds_bpermute_b32 v41, v69, v40
	s_waitcnt lgkmcnt(0)
	v_add_f32_e32 v40, v40, v41
	ds_bpermute_b32 v41, v70, v40
	s_waitcnt lgkmcnt(0)
; #define LAS __attribute__((address_space(3)))
; __device__ __forceinline__ unsigned pkbf(float a, float b) { bf16x2_t v = __builtin_convertvector((f32x2_t){a, b}, bf16x2_t); return __builtin_bit_cast(unsigned, v); }
; __device__ __forceinline__ void gdn_prep_phase(LAS unsigned char* lds, const GdnPrepArgs& A, int bid, int G, const unsigned char* zero_page) {
;     ...
;             float in[12][2];
; #pragma unroll
;             for (int i = 0; i < 12; ++i) { const unsigned u = *(const LAS unsigned*)(lds + L_PRE + ((p0 + i) * 3 + m) * 256 + lane * 4); in[i][0] = bflo(u); in[i][1] = bfhi(u); }
;             float y[8][2];
; #pragma unroll
;             for (int pp = 0; pp < 8; ++pp)
; #pragma unroll
;                 for (int c = 0; c < 2; ++c) { float s = 0.f;
; #pragma unroll
;                     for (int tau = 0; tau < 5; ++tau) s += wc[tau][c] * in[pp + tau][c];
;                     y[pp][c] = s * __builtin_amdgcn_rcpf(1.0f + __builtin_amdgcn_exp2f(-1.4426950408889634f * s)); }
;             if (m < 2) {
; #pragma unroll
;                 for (int pp = 0; pp < 8; ++pp) { float ss = row16_sum(y[pp][0] * y[pp][0] + y[pp][1] * y[pp][1]); ss += __shfl_xor(ss, 16); ss += __shfl_xor(ss, 32); const float rn = __builtin_amdgcn_rsqf(ss + EPS);
;                     *(LAS unsigned*)(lds + (m == 0 ? L_QN : L_KN) + (p0 + pp) * QS_ + lane * 4) = pkbf(y[pp][0] * rn, y[pp][1] * rn); }
;             } else {
; #pragma unroll
;                 for (int c = 0; c < 2; ++c) { v4u o; o.x = pkbf(y[0][c], y[1][c]); o.y = pkbf(y[2][c], y[3][c]); o.z = pkbf(y[4][c], y[5][c]); o.w = pkbf(y[6][c], y[7][c]);
;                     if (!(pflg & 8)) *(v4u*)(blob + B_VT + (2 * lane + c) * 128 + p0 * 2) = o; }
	v_add_f32_e32 v40, v40, v41
	v_add_f32_e32 v40, 0x358637bd, v40
	v_rsq_f32_e32 v40, v40
	s_nop 0
	v_pk_mul_f32 v[38:39], v[38:39], v[40:41] op_sel_hi:[1,0]
	s_nop 0
	v_cvt_pk_bf16_f32 v40, v38, v39
	v_mul_f32_e32 v38, 0xbfb8aa3b, v37
	v_exp_f32_e32 v38, v38
	s_nop 0
	v_add_f32_e32 v38, 1.0, v38
	v_rcp_f32_e32 v39, v38
	v_mul_f32_e32 v38, 0xbfb8aa3b, v36
	v_exp_f32_e32 v38, v38
	s_nop 0
	v_add_f32_e32 v38, 1.0, v38
	v_rcp_f32_e32 v38, v38
	s_nop 0
	v_pk_mul_f32 v[36:37], v[36:37], v[38:39]
	s_nop 0
	v_pk_mul_f32 v[38:39], v[36:37], v[36:37]
	s_nop 0
	v_add_f32_e32 v38, v38, v39
	s_nop 1
	v_add_f32_dpp v38, v38, v38 quad_perm:[1,0,3,2] row_mask:0xf bank_mask:0xf bound_ctrl:1
	s_nop 1
	v_add_f32_dpp v38, v38, v38 quad_perm:[2,3,0,1] row_mask:0xf bank_mask:0xf bound_ctrl:1
	s_nop 1
	v_add_f32_dpp v38, v38, v38 row_half_mirror row_mask:0xf bank_mask:0xf bound_ctrl:1
	s_nop 1
	v_add_f32_dpp v38, v38, v38 row_mirror row_mask:0xf bank_mask:0xf bound_ctrl:1
	ds_bpermute_b32 v39, v69, v38
	s_waitcnt lgkmcnt(0)
	v_add_f32_e32 v38, v38, v39
	ds_bpermute_b32 v39, v70, v38
	s_waitcnt lgkmcnt(0)
	v_add_f32_e32 v38, v38, v39
	v_add_f32_e32 v38, 0x358637bd, v38
	v_rsq_f32_e32 v38, v38
	s_nop 0
	v_pk_mul_f32 v[36:37], v[36:37], v[38:39] op_sel_hi:[1,0]
	s_nop 0
	v_cvt_pk_bf16_f32 v36, v36, v37
	v_add_u32_e32 v37, 0x400, v236
	ds_write2_b32 v37, v40, v36 offset0:16 offset1:84
	ds_read_b32 v46, v130 offset:8960
	ds_read_b32 v47, v233 offset:512
	v_and_b32_e32 v37, 0xffff0000, v16
	v_mov_b32_e32 v36, v33
	v_mov_b32_e32 v12, v37
	s_waitcnt lgkmcnt(1)
	v_and_b32_e32 v39, 0xffff0000, v46
	s_waitcnt lgkmcnt(0)
	v_and_b32_e32 v34, 0xffff0000, v47
	s_waitcnt vmcnt(4)
	v_pk_fma_f32 v[40:41], v[2:3], v[34:35], 0 op_sel:[1,0,0] op_sel_hi:[1,1,0]
	v_mov_b32_e32 v38, v13
	s_waitcnt vmcnt(3)
	v_pk_fma_f32 v[40:41], v[4:5], v[32:33], v[40:41] op_sel:[1,0,0]
	v_lshlrev_b32_e32 v17, 16, v46
	s_waitcnt vmcnt(2)
	v_pk_fma_f32 v[40:41], v[6:7], v[36:37], v[40:41] op_sel:[1,0,0]
	v_mov_b32_e32 v16, v15
	s_waitcnt vmcnt(1)
	v_pk_fma_f32 v[12:13], v[8:9], v[12:13], v[40:41] op_sel:[1,0,0]
	s_waitcnt vmcnt(0)
	v_pk_fma_f32 v[12:13], v[10:11], v[38:39], v[12:13] op_sel:[1,0,0]
	s_nop 0
	v_mul_f32_e32 v38, 0xbfb8aa3b, v13
	v_exp_f32_e32 v38, v38
	s_nop 0
	v_add_f32_e32 v38, 1.0, v38
	v_rcp_f32_e32 v39, v38
	v_mul_f32_e32 v38, 0xbfb8aa3b, v12
	v_exp_f32_e32 v38, v38
	s_nop 0
	v_add_f32_e32 v38, 1.0, v38
	v_rcp_f32_e32 v38, v38
	s_nop 0
	v_pk_mul_f32 v[12:13], v[12:13], v[38:39]
	v_lshlrev_b32_e32 v38, 16, v47
	v_mov_b32_e32 v39, v42
	v_pk_fma_f32 v[40:41], v[2:3], v[38:39], 0 op_sel_hi:[0,1,0]
	v_pk_fma_f32 v[40:41], v[4:5], v[42:43], v[40:41] op_sel_hi:[0,1,1]
	v_pk_fma_f32 v[40:41], v[6:7], v[44:45], v[40:41] op_sel_hi:[0,1,1]
	v_pk_fma_f32 v[14:15], v[8:9], v[14:15], v[40:41] op_sel_hi:[0,1,1]
	v_pk_fma_f32 v[14:15], v[10:11], v[16:17], v[14:15] op_sel_hi:[0,1,1]
	v_mul_f32_e32 v16, 0xbfb8aa3b, v15
	v_exp_f32_e32 v16, v16
	ds_read_b32 v46, v49 offset:512
	ds_read_b32 v47, v232 offset:512
	v_add_f32_e32 v16, 1.0, v16
	v_rcp_f32_e32 v17, v16
	v_mul_f32_e32 v16, 0xbfb8aa3b, v14
	v_exp_f32_e32 v16, v16
	s_waitcnt lgkmcnt(1)
	v_and_b32_e32 v41, 0xffff0000, v46
	s_waitcnt lgkmcnt(0)
	v_and_b32_e32 v40, 0xffff0000, v47
	v_pk_mov_b32 v[232:233], v[40:41], v[34:35] op_sel:[1,0]
	v_add_f32_e32 v16, 1.0, v16
	v_rcp_f32_e32 v16, v16
	s_nop 0
	v_pk_mul_f32 v[14:15], v[14:15], v[16:17]
	v_pk_fma_f32 v[16:17], v[2:3], v[40:41], 0 op_sel:[1,0,0] op_sel_hi:[1,1,0]
	s_nop 0
	v_pk_fma_f32 v[16:17], v[4:5], v[232:233], v[16:17] op_sel:[1,0,0]
	s_nop 0
	v_pk_fma_f32 v[16:17], v[6:7], v[34:35], v[16:17] op_sel:[1,0,0]
	s_nop 0
	v_pk_fma_f32 v[16:17], v[8:9], v[32:33], v[16:17] op_sel:[1,0,0]
	s_nop 0
	v_pk_fma_f32 v[16:17], v[10:11], v[36:37], v[16:17] op_sel:[1,0,0]
	v_lshlrev_b32_e32 v37, 16, v46
	v_mul_f32_e32 v32, 0xbfb8aa3b, v17
	v_exp_f32_e32 v32, v32
	v_lshlrev_b32_e32 v36, 16, v47
	v_pk_mov_b32 v[234:235], v[36:37], v[38:39] op_sel:[1,0]
	v_add_f32_e32 v32, 1.0, v32
	v_rcp_f32_e32 v33, v32
	v_mul_f32_e32 v32, 0xbfb8aa3b, v16
	v_exp_f32_e32 v32, v32
	s_nop 0
	v_add_f32_e32 v32, 1.0, v32
	v_rcp_f32_e32 v32, v32
	s_nop 0
	v_pk_mul_f32 v[16:17], v[16:17], v[32:33]
	v_pk_fma_f32 v[32:33], v[2:3], v[36:37], 0 op_sel_hi:[0,1,0]
	v_pk_fma_f32 v[32:33], v[4:5], v[234:235], v[32:33] op_sel_hi:[0,1,1]
	v_pk_fma_f32 v[32:33], v[6:7], v[38:39], v[32:33] op_sel_hi:[0,1,1]
	v_pk_fma_f32 v[32:33], v[8:9], v[42:43], v[32:33] op_sel_hi:[0,1,1]
	v_pk_fma_f32 v[32:33], v[10:11], v[44:45], v[32:33] op_sel_hi:[0,1,1]
	v_mul_f32_e32 v42, 0xbfb8aa3b, v33
	v_exp_f32_e32 v42, v42
	ds_read_b32 v44, v48 offset:512
	ds_read_b32 v45, v231 offset:512
	ds_read_b32 v230, v230 offset:512
	ds_read_b32 v130, v130 offset:512
	v_add_f32_e32 v42, 1.0, v42
	v_rcp_f32_e32 v43, v42
	v_mul_f32_e32 v42, 0xbfb8aa3b, v32
	v_exp_f32_e32 v42, v42
	s_waitcnt lgkmcnt(3)
	v_and_b32_e32 v47, 0xffff0000, v44
	s_waitcnt lgkmcnt(2)
; #define LAS __attribute__((address_space(3)))
; __device__ __forceinline__ unsigned pkbf(float a, float b) { bf16x2_t v = __builtin_convertvector((f32x2_t){a, b}, bf16x2_t); return __builtin_bit_cast(unsigned, v); }
; __device__ __forceinline__ void gdn_prep_phase(LAS unsigned char* lds, const GdnPrepArgs& A, int bid, int G, const unsigned char* zero_page) {
;     ...
;                 for (int c = 0; c < 2; ++c) { float s = 0.f;
; #pragma unroll
;                     for (int tau = 0; tau < 5; ++tau) s += wc[tau][c] * in[pp + tau][c];
;                     y[pp][c] = s * __builtin_amdgcn_rcpf(1.0f + __builtin_amdgcn_exp2f(-1.4426950408889634f * s)); }
;             if (m < 2) {
; #pragma unroll
;                 for (int pp = 0; pp < 8; ++pp) { float ss = row16_sum(y[pp][0] * y[pp][0] + y[pp][1] * y[pp][1]); ss += __shfl_xor(ss, 16); ss += __shfl_xor(ss, 32); const float rn = __builtin_amdgcn_rsqf(ss + EPS);
;                     *(LAS unsigned*)(lds + (m == 0 ? L_QN : L_KN) + (p0 + pp) * QS_ + lane * 4) = pkbf(y[pp][0] * rn, y[pp][1] * rn); }
;             } else {
; #pragma unroll
;                 for (int c = 0; c < 2; ++c) { v4u o; o.x = pkbf(y[0][c], y[1][c]); o.y = pkbf(y[2][c], y[3][c]); o.z = pkbf(y[4][c], y[5][c]); o.w = pkbf(y[6][c], y[7][c]);
;                     if (!(pflg & 8)) *(v4u*)(blob + B_VT + (2 * lane + c) * 128 + p0 * 2) = o; }
;             }
;         }
;     }
;     __syncthreads();
;     { const int un = unit + G; if (un < nunits) { gdn_prep_issue(lds, A, un, w, lane, zero_page); if (w == 0) smn = gdn_prep_scal(A, un, lane); } }
	v_and_b32_e32 v46, 0xffff0000, v45
	v_pk_mov_b32 v[48:49], v[46:47], v[40:41] op_sel:[1,0]
	v_add_f32_e32 v42, 1.0, v42
	v_rcp_f32_e32 v42, v42
	s_nop 0
	v_pk_mul_f32 v[32:33], v[32:33], v[42:43]
	v_pk_fma_f32 v[42:43], v[2:3], v[46:47], 0 op_sel:[1,0,0] op_sel_hi:[1,1,0]
	s_nop 0
	v_pk_fma_f32 v[42:43], v[4:5], v[48:49], v[42:43] op_sel:[1,0,0]
	s_nop 0
	v_pk_fma_f32 v[42:43], v[6:7], v[40:41], v[42:43] op_sel:[1,0,0]
	s_nop 0
	v_pk_fma_f32 v[42:43], v[8:9], v[232:233], v[42:43] op_sel:[1,0,0]
	s_nop 0
	v_pk_fma_f32 v[34:35], v[10:11], v[34:35], v[42:43] op_sel:[1,0,0]
	s_nop 0
	v_mul_f32_e32 v42, 0xbfb8aa3b, v35
	v_exp_f32_e32 v42, v42
	s_nop 0
	v_add_f32_e32 v42, 1.0, v42
	v_rcp_f32_e32 v43, v42
	v_mul_f32_e32 v42, 0xbfb8aa3b, v34
	v_exp_f32_e32 v42, v42
	s_nop 0
	v_add_f32_e32 v42, 1.0, v42
	v_rcp_f32_e32 v42, v42
	s_nop 0
	v_pk_mul_f32 v[34:35], v[34:35], v[42:43]
	v_lshlrev_b32_e32 v43, 16, v44
	v_lshlrev_b32_e32 v42, 16, v45
	v_pk_fma_f32 v[232:233], v[2:3], v[42:43], 0 op_sel_hi:[0,1,0]
	v_pk_mov_b32 v[44:45], v[42:43], v[36:37] op_sel:[1,0]
	s_nop 0
	v_pk_fma_f32 v[232:233], v[4:5], v[44:45], v[232:233] op_sel_hi:[0,1,1]
	v_pk_fma_f32 v[232:233], v[6:7], v[36:37], v[232:233] op_sel_hi:[0,1,1]
	v_pk_fma_f32 v[232:233], v[8:9], v[234:235], v[232:233] op_sel_hi:[0,1,1]
	v_pk_fma_f32 v[38:39], v[10:11], v[38:39], v[232:233] op_sel_hi:[0,1,1]
	v_mul_f32_e32 v231, 0xbfb8aa3b, v39
	v_exp_f32_e32 v231, v231
	s_nop 0
	v_add_f32_e32 v231, 1.0, v231
	v_rcp_f32_e32 v233, v231
	v_mul_f32_e32 v231, 0xbfb8aa3b, v38
	v_exp_f32_e32 v231, v231
	s_nop 0
	v_add_f32_e32 v231, 1.0, v231
	v_rcp_f32_e32 v232, v231
	s_nop 0
	v_pk_mul_f32 v[38:39], v[38:39], v[232:233]
	s_waitcnt lgkmcnt(1)
	v_and_b32_e32 v233, 0xffff0000, v230
	s_waitcnt lgkmcnt(0)
	v_and_b32_e32 v232, 0xffff0000, v130
	v_pk_fma_f32 v[234:235], v[2:3], v[232:233], 0 op_sel:[1,0,0] op_sel_hi:[1,1,0]
	v_pk_mov_b32 v[232:233], v[232:233], v[46:47] op_sel:[1,0]
	s_nop 0
	v_pk_fma_f32 v[232:233], v[4:5], v[232:233], v[234:235] op_sel:[1,0,0]
	s_nop 0
	v_pk_fma_f32 v[46:47], v[6:7], v[46:47], v[232:233] op_sel:[1,0,0]
	s_nop 0
	v_pk_fma_f32 v[46:47], v[8:9], v[48:49], v[46:47] op_sel:[1,0,0]
	s_nop 0
	v_pk_fma_f32 v[40:41], v[10:11], v[40:41], v[46:47] op_sel:[1,0,0]
	s_nop 0
	v_mul_f32_e32 v46, 0xbfb8aa3b, v41
	v_exp_f32_e32 v46, v46
	s_nop 0
	v_add_f32_e32 v46, 1.0, v46
	v_rcp_f32_e32 v47, v46
	v_mul_f32_e32 v46, 0xbfb8aa3b, v40
	v_exp_f32_e32 v46, v46
	s_nop 0
	v_add_f32_e32 v46, 1.0, v46
	v_rcp_f32_e32 v46, v46
	s_nop 0
	v_pk_mul_f32 v[40:41], v[40:41], v[46:47]
	v_lshlrev_b32_e32 v47, 16, v230
	v_lshlrev_b32_e32 v46, 16, v130
	v_pk_fma_f32 v[2:3], v[2:3], v[46:47], 0 op_sel_hi:[0,1,0]
	v_pk_mov_b32 v[46:47], v[46:47], v[42:43] op_sel:[1,0]
	s_nop 0
	v_pk_fma_f32 v[2:3], v[4:5], v[46:47], v[2:3] op_sel_hi:[0,1,1]
	v_pk_fma_f32 v[2:3], v[6:7], v[42:43], v[2:3] op_sel_hi:[0,1,1]
	v_pk_fma_f32 v[2:3], v[8:9], v[44:45], v[2:3] op_sel_hi:[0,1,1]
	v_pk_fma_f32 v[2:3], v[10:11], v[36:37], v[2:3] op_sel_hi:[0,1,1]
	v_mul_f32_e32 v4, 0xbfb8aa3b, v3
	v_exp_f32_e32 v4, v4
	v_lshl_add_u64 v[6:7], s[94:95], 0, v[20:21]
	v_lshl_add_u64 v[8:9], v[6:7], 0, s[42:43]
	s_mov_b32 s42, 0x14000
	v_add_f32_e32 v4, 1.0, v4
	v_rcp_f32_e32 v5, v4
	v_mul_f32_e32 v4, 0xbfb8aa3b, v2
	v_exp_f32_e32 v4, v4
	v_add_co_u32_e32 v6, vcc, s42, v6
	v_readlane_b32 s42, v254, 17
	v_add_f32_e32 v4, 1.0, v4
	v_rcp_f32_e32 v4, v4
	s_add_i32 s56, s56, s42
	s_cmpk_lt_i32 s56, 0x400
	s_cselect_b64 s[44:45], -1, 0
	v_pk_mul_f32 v[2:3], v[2:3], v[4:5]
	s_cmpk_gt_i32 s56, 0x3ff
	v_cvt_pk_bf16_f32 v2, v2, v3
	v_cvt_pk_bf16_f32 v3, v38, v39
	v_cvt_pk_bf16_f32 v4, v32, v33
	v_cvt_pk_bf16_f32 v5, v14, v15
	v_addc_co_u32_e32 v7, vcc, 0, v7, vcc
	s_cselect_b64 s[42:43], -1, 0
	global_store_dwordx4 v[6:7], v[2:5], off offset:2048
	s_and_b64 vcc, exec, s[42:43]
	s_nop 0
	v_cvt_pk_bf16_f32 v2, v40, v41
	v_cvt_pk_bf16_f32 v3, v34, v35
	v_cvt_pk_bf16_f32 v4, v16, v17
	v_cvt_pk_bf16_f32 v5, v12, v13
	global_store_dwordx4 v[8:9], v[2:5], off offset:128
	s_barrier
	s_cbranch_vccnz .LBB0_209
	v_readlane_b32 s46, v254, 59
	v_readlane_b32 s47, v254, 60
	s_andn2_b64 vcc, exec, s[46:47]
	s_cbranch_vccnz .LBB0_207
	s_ashr_i32 s46, s56, 31
	s_lshr_b32 s47, s46, 27
	s_add_i32 s48, s56, s47
	s_and_b32 s47, s48, 0x3ffffe0
	s_ashr_i32 s48, s48, 5
	s_lshr_b32 s49, s48, 29
	s_lshr_b32 s46, s46, 24
	s_add_i32 s49, s48, s49
	s_add_i32 s46, s56, s46
	s_and_b32 s49, s49, 0x1fffff8
	s_sub_i32 s47, s56, s47
	s_ashr_i32 s46, s46, 8
	s_sub_i32 s48, s48, s49
	s_lshl_b32 s57, s47, 6
	s_ashr_i32 s47, s46, 31
	s_lshl_b32 s94, s48, 7
	s_add_i32 s57, s57, -2
	s_lshl_b64 s[46:47], s[46:47], 22
	s_ashr_i32 s95, s94, 31
	v_readlane_b32 s48, v253, 48
	v_readlane_b32 s49, v253, 49
	s_add_u32 s46, s48, s46
	s_addc_u32 s47, s49, s47
	v_mov_b32_e32 v4, v189
	v_readlane_b32 s54, v255, 50
	v_readlane_b32 s55, v255, 47
	s_branch .LBB0_205
